# pipelined residual epilogue, batched adaLN GEMV loads, hand-written final/fft1/fft3 phases
# speedup vs baseline: 1.0410x; 1.0410x over previous
; __device__ __forceinline__ void fft3_phase(KP P, LAS unsigned char* lds, int l) {
;     ...
;     for (int it = bid_; it < 256; it += gridDim.x) {
;         const int b = it >> 7, k1 = (it & 127) >> 1, chh = it & 1, ch = 32 * (4 * chh + (w & 3)) + r32, mh = w >> 2;
;         const unsigned* zsrc = (const unsigned*)(ws + WS_ZS) + ((size_t)(b * 64 + k1) * 128 + 4 * hi) * 256 + ch;
;         f32x16 acc[2] = {};
; #pragma unroll
;         for (int sh = 0; sh < 2; ++sh) {
;             u32x4_t bfr[8];
; #pragma unroll
;             for (int s = 0; s < 8; ++s)
; #pragma unroll
;                 for (int j = 0; j < 4; ++j) bfr[s][j] = zsrc[(size_t)(8 * (8 * sh + s) + j) * 256];
; #pragma unroll
;             for (int s = 0; s < 8; ++s) {
;                 const bf16x8_t bf = __builtin_bit_cast(bf16x8_t, bfr[s]);
; #pragma unroll
;                 for (int mi = 0; mi < 2; ++mi) { const bf16x8_t af = *(const bf16x8_t*)(D3 + (32 * (2 * mh + mi) + r32) * 256 + 16 * (8 * sh + s) + 8 * hi);
;                     acc[mi] = __builtin_amdgcn_mfma_f32_32x32x16_bf16(af, bf, acc[mi], 0, 0, 0); }
;             }
.LBB0_33:
	s_andn2_b64 vcc, exec, s[6:7]
	s_mov_b32 s20, 0x8000
	s_cbranch_vccnz .LBB0_37
	v_mov_b32_e32 v0, v164
	s_mov_b32 s0, s98
	s_cmpk_gt_i32 s0, 0xff
	s_cbranch_scc1 .LBB0_37
	v_readlane_b32 s6, v254, 20
	v_readlane_b32 s7, v254, 21
	v_and_b32_e32 v156, 31, v164
	v_bfe_u32 v157, v164, 5, 1
	v_bfe_u32 v158, v164, 6, 2
	v_lshl_or_b32 v152, v158, 5, v156
	v_lshlrev_b32_e32 v155, 1, v152
	v_lshlrev_b32_e32 v152, 2, v152
	v_lshl_add_u32 v152, v157, 12, v152
	v_lshrrev_b32_e32 v158, 8, v164
	v_lshl_or_b32 v153, v158, 6, v156
	v_lshlrev_b32_e32 v153, 9, v153
	v_lshl_add_u32 v153, v157, 4, v153
	v_add_u32_e32 v154, 0x4000, v153
	v_lshl_or_b32 v158, v158, 4, v157
	v_lshl_add_u32 v155, v158, 19, v155
	s_mov_b32 s0, s98
.Lf3_item:
	s_cmpk_lt_i32 s0, 0x100
	s_cbranch_scc0 .Lf3_done
	s_lshr_b32 s2, s0, 7
	s_bfe_u32 s3, s0, 0x60001
	s_and_b32 s18, s0, 1
	s_lshl_b32 s12, s2, 6
	s_add_u32 s12, s12, s3
	s_lshl_b32 s12, s12, 17
	s_lshl_b32 s13, s18, 9
	s_add_u32 s12, s12, s13
	s_add_u32 s12, s12, 0xa100000
	s_add_u32 s12, s6, s12
	s_addc_u32 s13, s7, 0
	s_add_u32 s14, s6, 0xc030000
	s_addc_u32 s15, s7, 0
	global_load_dword v32, v152, s[12:13] offset:0
	global_load_dword v33, v152, s[12:13] offset:1024
	global_load_dword v34, v152, s[12:13] offset:2048
	global_load_dword v35, v152, s[12:13] offset:3072
	global_load_dwordx4 v[36:39], v153, s[14:15] offset:0
	global_load_dwordx4 v[40:43], v154, s[14:15] offset:0
	s_add_u32 s12, s12, 0x2000
	s_addc_u32 s13, s13, 0
	global_load_dword v44, v152, s[12:13] offset:0
	global_load_dword v45, v152, s[12:13] offset:1024
	global_load_dword v46, v152, s[12:13] offset:2048
	global_load_dword v47, v152, s[12:13] offset:3072
	global_load_dwordx4 v[48:51], v153, s[14:15] offset:32
	global_load_dwordx4 v[52:55], v154, s[14:15] offset:32
	s_add_u32 s12, s12, 0x2000
	s_addc_u32 s13, s13, 0
	global_load_dword v56, v152, s[12:13] offset:0
	global_load_dword v57, v152, s[12:13] offset:1024
	global_load_dword v58, v152, s[12:13] offset:2048
	global_load_dword v59, v152, s[12:13] offset:3072
	global_load_dwordx4 v[60:63], v153, s[14:15] offset:64
	global_load_dwordx4 v[64:67], v154, s[14:15] offset:64
	s_add_u32 s12, s12, 0x2000
	s_addc_u32 s13, s13, 0
	global_load_dword v68, v152, s[12:13] offset:0
	global_load_dword v69, v152, s[12:13] offset:1024
	global_load_dword v70, v152, s[12:13] offset:2048
	global_load_dword v71, v152, s[12:13] offset:3072
	global_load_dwordx4 v[72:75], v153, s[14:15] offset:96
	global_load_dwordx4 v[76:79], v154, s[14:15] offset:96
	s_add_u32 s12, s12, 0x2000
	s_addc_u32 s13, s13, 0
	global_load_dword v80, v152, s[12:13] offset:0
	global_load_dword v81, v152, s[12:13] offset:1024
	global_load_dword v82, v152, s[12:13] offset:2048
	global_load_dword v83, v152, s[12:13] offset:3072
	global_load_dwordx4 v[84:87], v153, s[14:15] offset:128
	global_load_dwordx4 v[88:91], v154, s[14:15] offset:128
	s_add_u32 s12, s12, 0x2000
	s_addc_u32 s13, s13, 0
	global_load_dword v92, v152, s[12:13] offset:0
	global_load_dword v93, v152, s[12:13] offset:1024
	global_load_dword v94, v152, s[12:13] offset:2048
	global_load_dword v95, v152, s[12:13] offset:3072
	global_load_dwordx4 v[96:99], v153, s[14:15] offset:160
	global_load_dwordx4 v[100:103], v154, s[14:15] offset:160
	s_add_u32 s12, s12, 0x2000
	s_addc_u32 s13, s13, 0
	global_load_dword v104, v152, s[12:13] offset:0
	global_load_dword v105, v152, s[12:13] offset:1024
	global_load_dword v106, v152, s[12:13] offset:2048
	global_load_dword v107, v152, s[12:13] offset:3072
	global_load_dwordx4 v[108:111], v153, s[14:15] offset:192
	global_load_dwordx4 v[112:115], v154, s[14:15] offset:192
	s_add_u32 s12, s12, 0x2000
	s_addc_u32 s13, s13, 0
	global_load_dword v116, v152, s[12:13] offset:0
	global_load_dword v117, v152, s[12:13] offset:1024
	global_load_dword v118, v152, s[12:13] offset:2048
	global_load_dword v119, v152, s[12:13] offset:3072
	global_load_dwordx4 v[120:123], v153, s[14:15] offset:224
	global_load_dwordx4 v[124:127], v154, s[14:15] offset:224
	s_add_u32 s12, s12, 0x2000
	s_addc_u32 s13, s13, 0
	global_load_dword v128, v152, s[12:13] offset:0
	global_load_dword v129, v152, s[12:13] offset:1024
	global_load_dword v130, v152, s[12:13] offset:2048
	global_load_dword v131, v152, s[12:13] offset:3072
	global_load_dwordx4 v[132:135], v153, s[14:15] offset:256
	global_load_dwordx4 v[136:139], v154, s[14:15] offset:256
	s_add_u32 s12, s12, 0x2000
	s_addc_u32 s13, s13, 0
	global_load_dword v140, v152, s[12:13] offset:0
	global_load_dword v141, v152, s[12:13] offset:1024
	global_load_dword v142, v152, s[12:13] offset:2048
	global_load_dword v143, v152, s[12:13] offset:3072
	global_load_dwordx4 v[144:147], v153, s[14:15] offset:288
	global_load_dwordx4 v[148:151], v154, s[14:15] offset:288
	s_add_u32 s12, s12, 0x2000
	s_addc_u32 s13, s13, 0
	v_mov_b32_e32 v0, 0
	v_mov_b32_e32 v1, 0
	v_mov_b32_e32 v2, 0
	v_mov_b32_e32 v3, 0
	v_mov_b32_e32 v4, 0
	v_mov_b32_e32 v5, 0
	v_mov_b32_e32 v6, 0
	v_mov_b32_e32 v7, 0
	v_mov_b32_e32 v8, 0
	v_mov_b32_e32 v9, 0
	v_mov_b32_e32 v10, 0
	v_mov_b32_e32 v11, 0
	v_mov_b32_e32 v12, 0
	v_mov_b32_e32 v13, 0
	v_mov_b32_e32 v14, 0
	v_mov_b32_e32 v15, 0
	v_mov_b32_e32 v16, 0
	v_mov_b32_e32 v17, 0
	v_mov_b32_e32 v18, 0
	v_mov_b32_e32 v19, 0
	v_mov_b32_e32 v20, 0
	v_mov_b32_e32 v21, 0
	v_mov_b32_e32 v22, 0
	v_mov_b32_e32 v23, 0
	v_mov_b32_e32 v24, 0
	v_mov_b32_e32 v25, 0
	v_mov_b32_e32 v26, 0
	v_mov_b32_e32 v27, 0
	v_mov_b32_e32 v28, 0
	v_mov_b32_e32 v29, 0
	v_mov_b32_e32 v30, 0
	v_mov_b32_e32 v31, 0
	s_waitcnt vmcnt(54)
; __device__ __forceinline__ void fft3_phase(KP P, LAS unsigned char* lds, int l) {
;     ...
;         for (int sh = 0; sh < 2; ++sh) {
;             u32x4_t bfr[8];
; #pragma unroll
;             for (int s = 0; s < 8; ++s)
; #pragma unroll
;                 for (int j = 0; j < 4; ++j) bfr[s][j] = zsrc[(size_t)(8 * (8 * sh + s) + j) * 256];
; #pragma unroll
;             for (int s = 0; s < 8; ++s) {
;                 const bf16x8_t bf = __builtin_bit_cast(bf16x8_t, bfr[s]);
; #pragma unroll
;                 for (int mi = 0; mi < 2; ++mi) { const bf16x8_t af = *(const bf16x8_t*)(D3 + (32 * (2 * mh + mi) + r32) * 256 + 16 * (8 * sh + s) + 8 * hi);
;                     acc[mi] = __builtin_amdgcn_mfma_f32_32x32x16_bf16(af, bf, acc[mi], 0, 0, 0); }
;             }
	v_mfma_f32_32x32x16_bf16 v[0:15], v[36:39], v[32:35], v[0:15]
	v_mfma_f32_32x32x16_bf16 v[16:31], v[40:43], v[32:35], v[16:31]
	s_nop 1
	global_load_dword v32, v152, s[12:13] offset:0
	global_load_dword v33, v152, s[12:13] offset:1024
	global_load_dword v34, v152, s[12:13] offset:2048
	global_load_dword v35, v152, s[12:13] offset:3072
	global_load_dwordx4 v[36:39], v153, s[14:15] offset:320
	global_load_dwordx4 v[40:43], v154, s[14:15] offset:320
	s_add_u32 s12, s12, 0x2000
	s_addc_u32 s13, s13, 0
	s_waitcnt vmcnt(54)
	v_mfma_f32_32x32x16_bf16 v[0:15], v[48:51], v[44:47], v[0:15]
	v_mfma_f32_32x32x16_bf16 v[16:31], v[52:55], v[44:47], v[16:31]
	s_nop 1
	global_load_dword v44, v152, s[12:13] offset:0
	global_load_dword v45, v152, s[12:13] offset:1024
	global_load_dword v46, v152, s[12:13] offset:2048
	global_load_dword v47, v152, s[12:13] offset:3072
	global_load_dwordx4 v[48:51], v153, s[14:15] offset:352
	global_load_dwordx4 v[52:55], v154, s[14:15] offset:352
	s_add_u32 s12, s12, 0x2000
	s_addc_u32 s13, s13, 0
	s_waitcnt vmcnt(54)
	v_mfma_f32_32x32x16_bf16 v[0:15], v[60:63], v[56:59], v[0:15]
	v_mfma_f32_32x32x16_bf16 v[16:31], v[64:67], v[56:59], v[16:31]
	s_nop 1
	global_load_dword v56, v152, s[12:13] offset:0
	global_load_dword v57, v152, s[12:13] offset:1024
	global_load_dword v58, v152, s[12:13] offset:2048
	global_load_dword v59, v152, s[12:13] offset:3072
	global_load_dwordx4 v[60:63], v153, s[14:15] offset:384
	global_load_dwordx4 v[64:67], v154, s[14:15] offset:384
	s_add_u32 s12, s12, 0x2000
	s_addc_u32 s13, s13, 0
	s_waitcnt vmcnt(54)
	v_mfma_f32_32x32x16_bf16 v[0:15], v[72:75], v[68:71], v[0:15]
	v_mfma_f32_32x32x16_bf16 v[16:31], v[76:79], v[68:71], v[16:31]
	s_nop 1
	global_load_dword v68, v152, s[12:13] offset:0
	global_load_dword v69, v152, s[12:13] offset:1024
	global_load_dword v70, v152, s[12:13] offset:2048
	global_load_dword v71, v152, s[12:13] offset:3072
	global_load_dwordx4 v[72:75], v153, s[14:15] offset:416
	global_load_dwordx4 v[76:79], v154, s[14:15] offset:416
	s_add_u32 s12, s12, 0x2000
	s_addc_u32 s13, s13, 0
	s_waitcnt vmcnt(54)
	v_mfma_f32_32x32x16_bf16 v[0:15], v[84:87], v[80:83], v[0:15]
	v_mfma_f32_32x32x16_bf16 v[16:31], v[88:91], v[80:83], v[16:31]
	s_nop 1
	global_load_dword v80, v152, s[12:13] offset:0
	global_load_dword v81, v152, s[12:13] offset:1024
	global_load_dword v82, v152, s[12:13] offset:2048
	global_load_dword v83, v152, s[12:13] offset:3072
	global_load_dwordx4 v[84:87], v153, s[14:15] offset:448
	global_load_dwordx4 v[88:91], v154, s[14:15] offset:448
	s_add_u32 s12, s12, 0x2000
	s_addc_u32 s13, s13, 0
	s_waitcnt vmcnt(54)
	v_mfma_f32_32x32x16_bf16 v[0:15], v[96:99], v[92:95], v[0:15]
	v_mfma_f32_32x32x16_bf16 v[16:31], v[100:103], v[92:95], v[16:31]
	s_nop 1
	global_load_dword v92, v152, s[12:13] offset:0
	global_load_dword v93, v152, s[12:13] offset:1024
	global_load_dword v94, v152, s[12:13] offset:2048
	global_load_dword v95, v152, s[12:13] offset:3072
	global_load_dwordx4 v[96:99], v153, s[14:15] offset:480
	global_load_dwordx4 v[100:103], v154, s[14:15] offset:480
	s_add_u32 s12, s12, 0x2000
	s_addc_u32 s13, s13, 0
	s_waitcnt vmcnt(54)
	v_mfma_f32_32x32x16_bf16 v[0:15], v[108:111], v[104:107], v[0:15]
	v_mfma_f32_32x32x16_bf16 v[16:31], v[112:115], v[104:107], v[16:31]
	s_waitcnt vmcnt(48)
	v_mfma_f32_32x32x16_bf16 v[0:15], v[120:123], v[116:119], v[0:15]
	v_mfma_f32_32x32x16_bf16 v[16:31], v[124:127], v[116:119], v[16:31]
	s_waitcnt vmcnt(42)
	v_mfma_f32_32x32x16_bf16 v[0:15], v[132:135], v[128:131], v[0:15]
	v_mfma_f32_32x32x16_bf16 v[16:31], v[136:139], v[128:131], v[16:31]
	s_waitcnt vmcnt(36)
	v_mfma_f32_32x32x16_bf16 v[0:15], v[144:147], v[140:143], v[0:15]
	v_mfma_f32_32x32x16_bf16 v[16:31], v[148:151], v[140:143], v[16:31]
	s_waitcnt vmcnt(30)
	v_mfma_f32_32x32x16_bf16 v[0:15], v[36:39], v[32:35], v[0:15]
	v_mfma_f32_32x32x16_bf16 v[16:31], v[40:43], v[32:35], v[16:31]
	s_waitcnt vmcnt(24)
	v_mfma_f32_32x32x16_bf16 v[0:15], v[48:51], v[44:47], v[0:15]
	v_mfma_f32_32x32x16_bf16 v[16:31], v[52:55], v[44:47], v[16:31]
	s_waitcnt vmcnt(18)
	v_mfma_f32_32x32x16_bf16 v[0:15], v[60:63], v[56:59], v[0:15]
	v_mfma_f32_32x32x16_bf16 v[16:31], v[64:67], v[56:59], v[16:31]
	s_waitcnt vmcnt(12)
	v_mfma_f32_32x32x16_bf16 v[0:15], v[72:75], v[68:71], v[0:15]
	v_mfma_f32_32x32x16_bf16 v[16:31], v[76:79], v[68:71], v[16:31]
	s_waitcnt vmcnt(6)
	v_mfma_f32_32x32x16_bf16 v[0:15], v[84:87], v[80:83], v[0:15]
	v_mfma_f32_32x32x16_bf16 v[16:31], v[88:91], v[80:83], v[16:31]
	s_waitcnt vmcnt(0)
; __device__ __forceinline__ bf16_t f2bf(float f) { unsigned u = __float_as_uint(f); return (bf16_t)((u + 0x7fffu + ((u >> 16) & 1u)) >> 16); }
; __device__ __forceinline__ void fft3_phase(KP P, LAS unsigned char* lds, int l) {
;     ...
;     for (int it = bid_; it < 256; it += gridDim.x) {
;     ...
; #pragma unroll
;         for (int mi = 0; mi < 2; ++mi)
; #pragma unroll
;             for (int r = 0; r < 16; ++r) { const int k2 = 32 * (2 * mh + mi) + (r & 3) + 8 * (r >> 2) + 4 * hi;
;                 OM[((size_t)b * RPB + k1 + 64 * k2) * DM + 768 + ch] = f2bf(acc[mi][r] * 0.0013810679320049757f); }
	v_mfma_f32_32x32x16_bf16 v[0:15], v[96:99], v[92:95], v[0:15]
	v_mfma_f32_32x32x16_bf16 v[16:31], v[100:103], v[92:95], v[16:31]
	s_mul_i32 s2, s2, 0x2100
	s_add_u32 s2, s2, s3
	s_lshl_b32 s2, s2, 11
	s_lshl_b32 s18, s18, 8
	s_add_u32 s2, s2, s18
	s_add_u32 s2, s2, 0x4200600
	s_add_u32 s18, s6, s2
	s_addc_u32 s19, s7, 0
	s_nop 7
	s_nop 7
	v_mul_f32_e32 v156, 0x3ab504f3, v0
	v_bfe_u32 v157, v156, 16, 1
	v_add3_u32 v159, v156, v157, s44
	global_store_short_d16_hi v155, v159, s[18:19]
	s_add_u32 s18, s18, 0x20000
	s_addc_u32 s19, s19, 0
	v_mul_f32_e32 v156, 0x3ab504f3, v1
	v_bfe_u32 v157, v156, 16, 1
	v_add3_u32 v158, v156, v157, s44
	global_store_short_d16_hi v155, v158, s[18:19]
	s_add_u32 s18, s18, 0x20000
	s_addc_u32 s19, s19, 0
	v_mul_f32_e32 v156, 0x3ab504f3, v2
	v_bfe_u32 v157, v156, 16, 1
	v_add3_u32 v159, v156, v157, s44
	global_store_short_d16_hi v155, v159, s[18:19]
	s_add_u32 s18, s18, 0x20000
	s_addc_u32 s19, s19, 0
	v_mul_f32_e32 v156, 0x3ab504f3, v3
	v_bfe_u32 v157, v156, 16, 1
	v_add3_u32 v158, v156, v157, s44
	global_store_short_d16_hi v155, v158, s[18:19]
	s_add_u32 s18, s18, 0xa0000
	s_addc_u32 s19, s19, 0
	v_mul_f32_e32 v156, 0x3ab504f3, v4
	v_bfe_u32 v157, v156, 16, 1
	v_add3_u32 v159, v156, v157, s44
	global_store_short_d16_hi v155, v159, s[18:19]
	s_add_u32 s18, s18, 0x20000
	s_addc_u32 s19, s19, 0
	v_mul_f32_e32 v156, 0x3ab504f3, v5
	v_bfe_u32 v157, v156, 16, 1
	v_add3_u32 v158, v156, v157, s44
	global_store_short_d16_hi v155, v158, s[18:19]
	s_add_u32 s18, s18, 0x20000
	s_addc_u32 s19, s19, 0
	v_mul_f32_e32 v156, 0x3ab504f3, v6
	v_bfe_u32 v157, v156, 16, 1
	v_add3_u32 v159, v156, v157, s44
	global_store_short_d16_hi v155, v159, s[18:19]
	s_add_u32 s18, s18, 0x20000
	s_addc_u32 s19, s19, 0
	v_mul_f32_e32 v156, 0x3ab504f3, v7
	v_bfe_u32 v157, v156, 16, 1
	v_add3_u32 v158, v156, v157, s44
	global_store_short_d16_hi v155, v158, s[18:19]
	s_add_u32 s18, s18, 0xa0000
	s_addc_u32 s19, s19, 0
	v_mul_f32_e32 v156, 0x3ab504f3, v8
	v_bfe_u32 v157, v156, 16, 1
	v_add3_u32 v159, v156, v157, s44
	global_store_short_d16_hi v155, v159, s[18:19]
	s_add_u32 s18, s18, 0x20000
	s_addc_u32 s19, s19, 0
	v_mul_f32_e32 v156, 0x3ab504f3, v9
	v_bfe_u32 v157, v156, 16, 1
	v_add3_u32 v158, v156, v157, s44
	global_store_short_d16_hi v155, v158, s[18:19]
	s_add_u32 s18, s18, 0x20000
	s_addc_u32 s19, s19, 0
	v_mul_f32_e32 v156, 0x3ab504f3, v10
	v_bfe_u32 v157, v156, 16, 1
	v_add3_u32 v159, v156, v157, s44
	global_store_short_d16_hi v155, v159, s[18:19]
	s_add_u32 s18, s18, 0x20000
	s_addc_u32 s19, s19, 0
	v_mul_f32_e32 v156, 0x3ab504f3, v11
	v_bfe_u32 v157, v156, 16, 1
	v_add3_u32 v158, v156, v157, s44
	global_store_short_d16_hi v155, v158, s[18:19]
	s_add_u32 s18, s18, 0xa0000
	s_addc_u32 s19, s19, 0
	v_mul_f32_e32 v156, 0x3ab504f3, v12
	v_bfe_u32 v157, v156, 16, 1
	v_add3_u32 v159, v156, v157, s44
	global_store_short_d16_hi v155, v159, s[18:19]
	s_add_u32 s18, s18, 0x20000
	s_addc_u32 s19, s19, 0
	v_mul_f32_e32 v156, 0x3ab504f3, v13
	v_bfe_u32 v157, v156, 16, 1
	v_add3_u32 v158, v156, v157, s44
	global_store_short_d16_hi v155, v158, s[18:19]
	s_add_u32 s18, s18, 0x20000
	s_addc_u32 s19, s19, 0
	v_mul_f32_e32 v156, 0x3ab504f3, v14
	v_bfe_u32 v157, v156, 16, 1
	v_add3_u32 v159, v156, v157, s44
	global_store_short_d16_hi v155, v159, s[18:19]
	s_add_u32 s18, s18, 0x20000
	s_addc_u32 s19, s19, 0
	v_mul_f32_e32 v156, 0x3ab504f3, v15
	v_bfe_u32 v157, v156, 16, 1
	v_add3_u32 v158, v156, v157, s44
	global_store_short_d16_hi v155, v158, s[18:19]
	s_add_u32 s18, s18, 0xa0000
	s_addc_u32 s19, s19, 0
	v_mul_f32_e32 v156, 0x3ab504f3, v16
	v_bfe_u32 v157, v156, 16, 1
	v_add3_u32 v159, v156, v157, s44
	global_store_short_d16_hi v155, v159, s[18:19]
	s_add_u32 s18, s18, 0x20000
	s_addc_u32 s19, s19, 0
	v_mul_f32_e32 v156, 0x3ab504f3, v17
	v_bfe_u32 v157, v156, 16, 1
	v_add3_u32 v158, v156, v157, s44
	global_store_short_d16_hi v155, v158, s[18:19]
	s_add_u32 s18, s18, 0x20000
	s_addc_u32 s19, s19, 0
	v_mul_f32_e32 v156, 0x3ab504f3, v18
	v_bfe_u32 v157, v156, 16, 1
	v_add3_u32 v159, v156, v157, s44
	global_store_short_d16_hi v155, v159, s[18:19]
	s_add_u32 s18, s18, 0x20000
	s_addc_u32 s19, s19, 0
	v_mul_f32_e32 v156, 0x3ab504f3, v19
	v_bfe_u32 v157, v156, 16, 1
	v_add3_u32 v158, v156, v157, s44
	global_store_short_d16_hi v155, v158, s[18:19]
	s_add_u32 s18, s18, 0xa0000
	s_addc_u32 s19, s19, 0
	v_mul_f32_e32 v156, 0x3ab504f3, v20
	v_bfe_u32 v157, v156, 16, 1
	v_add3_u32 v159, v156, v157, s44
	global_store_short_d16_hi v155, v159, s[18:19]
	s_add_u32 s18, s18, 0x20000
	s_addc_u32 s19, s19, 0
	v_mul_f32_e32 v156, 0x3ab504f3, v21
	v_bfe_u32 v157, v156, 16, 1
	v_add3_u32 v158, v156, v157, s44
	global_store_short_d16_hi v155, v158, s[18:19]
	s_add_u32 s18, s18, 0x20000
	s_addc_u32 s19, s19, 0
	v_mul_f32_e32 v156, 0x3ab504f3, v22
	v_bfe_u32 v157, v156, 16, 1
	v_add3_u32 v159, v156, v157, s44
	global_store_short_d16_hi v155, v159, s[18:19]
	s_add_u32 s18, s18, 0x20000
	s_addc_u32 s19, s19, 0
	v_mul_f32_e32 v156, 0x3ab504f3, v23
	v_bfe_u32 v157, v156, 16, 1
	v_add3_u32 v158, v156, v157, s44
	global_store_short_d16_hi v155, v158, s[18:19]
	s_add_u32 s18, s18, 0xa0000
	s_addc_u32 s19, s19, 0
	v_mul_f32_e32 v156, 0x3ab504f3, v24
	v_bfe_u32 v157, v156, 16, 1
	v_add3_u32 v159, v156, v157, s44
	global_store_short_d16_hi v155, v159, s[18:19]
	s_add_u32 s18, s18, 0x20000
	s_addc_u32 s19, s19, 0
	v_mul_f32_e32 v156, 0x3ab504f3, v25
	v_bfe_u32 v157, v156, 16, 1
	v_add3_u32 v158, v156, v157, s44
	global_store_short_d16_hi v155, v158, s[18:19]
	s_add_u32 s18, s18, 0x20000
	s_addc_u32 s19, s19, 0
	v_mul_f32_e32 v156, 0x3ab504f3, v26
	v_bfe_u32 v157, v156, 16, 1
	v_add3_u32 v159, v156, v157, s44
	global_store_short_d16_hi v155, v159, s[18:19]
	s_add_u32 s18, s18, 0x20000
	s_addc_u32 s19, s19, 0
	v_mul_f32_e32 v156, 0x3ab504f3, v27
	v_bfe_u32 v157, v156, 16, 1
	v_add3_u32 v158, v156, v157, s44
	global_store_short_d16_hi v155, v158, s[18:19]
	s_add_u32 s18, s18, 0xa0000
	s_addc_u32 s19, s19, 0
	v_mul_f32_e32 v156, 0x3ab504f3, v28
	v_bfe_u32 v157, v156, 16, 1
	v_add3_u32 v159, v156, v157, s44
	global_store_short_d16_hi v155, v159, s[18:19]
	s_add_u32 s18, s18, 0x20000
	s_addc_u32 s19, s19, 0
	v_mul_f32_e32 v156, 0x3ab504f3, v29
	v_bfe_u32 v157, v156, 16, 1
	v_add3_u32 v158, v156, v157, s44
	global_store_short_d16_hi v155, v158, s[18:19]
	s_add_u32 s18, s18, 0x20000
	s_addc_u32 s19, s19, 0
	v_mul_f32_e32 v156, 0x3ab504f3, v30
	v_bfe_u32 v157, v156, 16, 1
	v_add3_u32 v159, v156, v157, s44
	global_store_short_d16_hi v155, v159, s[18:19]
	s_add_u32 s18, s18, 0x20000
	s_addc_u32 s19, s19, 0
	v_mul_f32_e32 v156, 0x3ab504f3, v31
	v_bfe_u32 v157, v156, 16, 1
	v_add3_u32 v158, v156, v157, s44
	global_store_short_d16_hi v155, v158, s[18:19]
	s_load_dword s2, s[72:73], 0x0
	s_waitcnt lgkmcnt(0)
	s_add_i32 s0, s0, s2
	s_branch .Lf3_item
; __device__ __forceinline__ void fft1_phase(KP P, int l) {
;     ...
;     for (int it = bid_; it < 256; it += gridDim.x) {
;         const int b = it >> 7, l2 = it & 127, ch = 32 * w + r32;
;         const unsigned* vsrc = (const unsigned*)(ws + WS_VS) + ((size_t)(b * SEQ + l2 + 512 * hi)) * 256 + ch;
;         u32x4_t bfr[8];
; #pragma unroll
;         for (int s = 0; s < 8; ++s)
; #pragma unroll
;             for (int j = 0; j < 4; ++j) bfr[s][j] = vsrc[(size_t)(128 * (8 * s + j)) * 256];
;         f32x16 acc[4] = {};
; #pragma unroll
;         for (int s = 0; s < 8; ++s) {
;             const bf16x8_t bf = __builtin_bit_cast(bf16x8_t, bfr[s]);
; #pragma unroll
;             for (int mt = 0; mt < 4; ++mt) { const bf16x8_t af = *(const bf16x8_t*)(D1 + (32 * mt + r32) * 128 + 16 * s + 8 * hi);
;                 acc[mt] = __builtin_amdgcn_mfma_f32_32x32x16_bf16(af, bf, acc[mt], 0, 0, 0); }
.Lf3_done:
.LBB0_37:
	s_mov_b64 s[6:7], 0
.LBB0_38:
	s_and_b64 vcc, exec, s[6:7]
	s_cbranch_vccz .LBB0_115
	s_cmp_gt_i32 s22, 4
	s_mov_b64 s[6:7], -1
	s_cbranch_scc0 .LBB0_110
	v_readlane_b32 s2, v254, 18
	v_mov_b32_e32 v146, v164
	s_mov_b32 s0, s98
	v_readlane_b32 s3, v254, 19
	s_load_dwordx2 s[2:3], s[2:3], 0xb8
	s_waitcnt lgkmcnt(0)
	s_add_u32 s6, s2, 0xc018000
	s_addc_u32 s7, s3, 0
	s_cmpk_gt_i32 s0, 0xff
	s_cbranch_scc1 .LBB0_43
	v_readlane_b32 s12, v254, 20
	v_readlane_b32 s13, v254, 21
	v_and_b32_e32 v177, 31, v164
	v_bfe_u32 v176, v164, 5, 1
	v_lshrrev_b32_e32 v178, 6, v164
	v_lshl_or_b32 v178, v178, 5, v177
	v_lshlrev_b32_e32 v178, 2, v178
	v_lshl_add_u32 v170, v176, 19, v178
	v_lshl_add_u32 v175, v176, 18, v178
	v_lshlrev_b32_e32 v171, 8, v177
	v_lshl_add_u32 v171, v176, 4, v171
	v_add_u32_e32 v172, 0x2000, v171
	v_add_u32_e32 v173, 0x4000, v171
	v_add_u32_e32 v174, 0x6000, v171
	s_mov_b32 s26, s0
.Lf1_item:
	s_cmpk_lt_i32 s26, 0x100
	s_cbranch_scc0 .Lf1_done
	s_lshr_b32 s2, s26, 7
	s_and_b32 s3, s26, 0x7f
	s_lshl_b32 s14, s2, 13
	s_add_u32 s14, s14, s3
	s_lshl_b32 s14, s14, 10
	s_add_u32 s14, s14, 0x9100000
	s_add_u32 s14, s12, s14
	s_addc_u32 s15, s13, 0
	global_load_dword v64, v170, s[14:15]
	s_add_u32 s14, s14, 0x20000
	s_addc_u32 s15, s15, 0
	global_load_dword v65, v170, s[14:15]
	s_add_u32 s14, s14, 0x20000
	s_addc_u32 s15, s15, 0
	global_load_dword v66, v170, s[14:15]
	s_add_u32 s14, s14, 0x20000
	s_addc_u32 s15, s15, 0
	global_load_dword v67, v170, s[14:15]
	s_add_u32 s14, s14, 0xa0000
	s_addc_u32 s15, s15, 0
	global_load_dword v68, v170, s[14:15]
	s_add_u32 s14, s14, 0x20000
	s_addc_u32 s15, s15, 0
	global_load_dword v69, v170, s[14:15]
	s_add_u32 s14, s14, 0x20000
	s_addc_u32 s15, s15, 0
	global_load_dword v70, v170, s[14:15]
	s_add_u32 s14, s14, 0x20000
	s_addc_u32 s15, s15, 0
	global_load_dword v71, v170, s[14:15]
	s_add_u32 s14, s14, 0xa0000
	s_addc_u32 s15, s15, 0
	global_load_dword v72, v170, s[14:15]
	s_add_u32 s14, s14, 0x20000
	s_addc_u32 s15, s15, 0
	global_load_dword v73, v170, s[14:15]
	s_add_u32 s14, s14, 0x20000
	s_addc_u32 s15, s15, 0
	global_load_dword v74, v170, s[14:15]
	s_add_u32 s14, s14, 0x20000
	s_addc_u32 s15, s15, 0
	global_load_dword v75, v170, s[14:15]
	s_add_u32 s14, s14, 0xa0000
	s_addc_u32 s15, s15, 0
	global_load_dword v76, v170, s[14:15]
	s_add_u32 s14, s14, 0x20000
	s_addc_u32 s15, s15, 0
	global_load_dword v77, v170, s[14:15]
	s_add_u32 s14, s14, 0x20000
	s_addc_u32 s15, s15, 0
	global_load_dword v78, v170, s[14:15]
	s_add_u32 s14, s14, 0x20000
	s_addc_u32 s15, s15, 0
	global_load_dword v79, v170, s[14:15]
	s_add_u32 s14, s14, 0xa0000
	s_addc_u32 s15, s15, 0
	global_load_dword v80, v170, s[14:15]
	s_add_u32 s14, s14, 0x20000
	s_addc_u32 s15, s15, 0
	global_load_dword v81, v170, s[14:15]
	s_add_u32 s14, s14, 0x20000
	s_addc_u32 s15, s15, 0
	global_load_dword v82, v170, s[14:15]
	s_add_u32 s14, s14, 0x20000
	s_addc_u32 s15, s15, 0
	global_load_dword v83, v170, s[14:15]
	s_add_u32 s14, s14, 0xa0000
	s_addc_u32 s15, s15, 0
	global_load_dword v84, v170, s[14:15]
	s_add_u32 s14, s14, 0x20000
	s_addc_u32 s15, s15, 0
	global_load_dword v85, v170, s[14:15]
	s_add_u32 s14, s14, 0x20000
	s_addc_u32 s15, s15, 0
	global_load_dword v86, v170, s[14:15]
	s_add_u32 s14, s14, 0x20000
	s_addc_u32 s15, s15, 0
	global_load_dword v87, v170, s[14:15]
	s_add_u32 s14, s14, 0xa0000
	s_addc_u32 s15, s15, 0
	global_load_dword v88, v170, s[14:15]
	s_add_u32 s14, s14, 0x20000
	s_addc_u32 s15, s15, 0
	global_load_dword v89, v170, s[14:15]
	s_add_u32 s14, s14, 0x20000
	s_addc_u32 s15, s15, 0
	global_load_dword v90, v170, s[14:15]
	s_add_u32 s14, s14, 0x20000
	s_addc_u32 s15, s15, 0
	global_load_dword v91, v170, s[14:15]
	s_add_u32 s14, s14, 0xa0000
	s_addc_u32 s15, s15, 0
	global_load_dword v92, v170, s[14:15]
	s_add_u32 s14, s14, 0x20000
	s_addc_u32 s15, s15, 0
	global_load_dword v93, v170, s[14:15]
	s_add_u32 s14, s14, 0x20000
	s_addc_u32 s15, s15, 0
	global_load_dword v94, v170, s[14:15]
	s_add_u32 s14, s14, 0x20000
	s_addc_u32 s15, s15, 0
	global_load_dword v95, v170, s[14:15]
	s_add_u32 s14, s14, 0xa0000
	s_addc_u32 s15, s15, 0
	s_add_u32 s2, s12, 0xc028000
	s_addc_u32 s3, s13, 0
	global_load_dwordx4 v[96:99], v171, s[2:3] offset:0
	global_load_dwordx4 v[100:103], v172, s[2:3] offset:0
	global_load_dwordx4 v[104:107], v173, s[2:3] offset:0
	global_load_dwordx4 v[108:111], v174, s[2:3] offset:0
	global_load_dwordx4 v[112:115], v171, s[2:3] offset:32
	global_load_dwordx4 v[116:119], v172, s[2:3] offset:32
	global_load_dwordx4 v[120:123], v173, s[2:3] offset:32
	global_load_dwordx4 v[124:127], v174, s[2:3] offset:32
	global_load_dwordx4 v[128:131], v171, s[2:3] offset:64
	global_load_dwordx4 v[132:135], v172, s[2:3] offset:64
	global_load_dwordx4 v[136:139], v173, s[2:3] offset:64
	global_load_dwordx4 v[140:143], v174, s[2:3] offset:64
	global_load_dwordx4 v[148:151], v171, s[2:3] offset:96
	global_load_dwordx4 v[152:155], v172, s[2:3] offset:96
	global_load_dwordx4 v[156:159], v173, s[2:3] offset:96
	global_load_dwordx4 v[160:163], v174, s[2:3] offset:96
	v_mov_b32_e32 v0, 0
	v_mov_b32_e32 v1, 0
	v_mov_b32_e32 v2, 0
	v_mov_b32_e32 v3, 0
	v_mov_b32_e32 v4, 0
	v_mov_b32_e32 v5, 0
	v_mov_b32_e32 v6, 0
	v_mov_b32_e32 v7, 0
	v_mov_b32_e32 v8, 0
	v_mov_b32_e32 v9, 0
	v_mov_b32_e32 v10, 0
	v_mov_b32_e32 v11, 0
	v_mov_b32_e32 v12, 0
	v_mov_b32_e32 v13, 0
	v_mov_b32_e32 v14, 0
	v_mov_b32_e32 v15, 0
	v_mov_b32_e32 v16, 0
	v_mov_b32_e32 v17, 0
	v_mov_b32_e32 v18, 0
	v_mov_b32_e32 v19, 0
	v_mov_b32_e32 v20, 0
	v_mov_b32_e32 v21, 0
	v_mov_b32_e32 v22, 0
	v_mov_b32_e32 v23, 0
	v_mov_b32_e32 v24, 0
	v_mov_b32_e32 v25, 0
	v_mov_b32_e32 v26, 0
	v_mov_b32_e32 v27, 0
	v_mov_b32_e32 v28, 0
	v_mov_b32_e32 v29, 0
	v_mov_b32_e32 v30, 0
	v_mov_b32_e32 v31, 0
	v_mov_b32_e32 v32, 0
	v_mov_b32_e32 v33, 0
	v_mov_b32_e32 v34, 0
	v_mov_b32_e32 v35, 0
	v_mov_b32_e32 v36, 0
	v_mov_b32_e32 v37, 0
	v_mov_b32_e32 v38, 0
	v_mov_b32_e32 v39, 0
	v_mov_b32_e32 v40, 0
	v_mov_b32_e32 v41, 0
	v_mov_b32_e32 v42, 0
	v_mov_b32_e32 v43, 0
	v_mov_b32_e32 v44, 0
	v_mov_b32_e32 v45, 0
	v_mov_b32_e32 v46, 0
	v_mov_b32_e32 v47, 0
	v_mov_b32_e32 v48, 0
	v_mov_b32_e32 v49, 0
	v_mov_b32_e32 v50, 0
	v_mov_b32_e32 v51, 0
	v_mov_b32_e32 v52, 0
	v_mov_b32_e32 v53, 0
	v_mov_b32_e32 v54, 0
	v_mov_b32_e32 v55, 0
	v_mov_b32_e32 v56, 0
	v_mov_b32_e32 v57, 0
	v_mov_b32_e32 v58, 0
	v_mov_b32_e32 v59, 0
	v_mov_b32_e32 v60, 0
	v_mov_b32_e32 v61, 0
	v_mov_b32_e32 v62, 0
	v_mov_b32_e32 v63, 0
	s_waitcnt vmcnt(12)
; __device__ __forceinline__ void fft1_phase(KP P, int l) {
;     ...
; #pragma unroll
;         for (int s = 0; s < 8; ++s) {
;             const bf16x8_t bf = __builtin_bit_cast(bf16x8_t, bfr[s]);
; #pragma unroll
;             for (int mt = 0; mt < 4; ++mt) { const bf16x8_t af = *(const bf16x8_t*)(D1 + (32 * mt + r32) * 128 + 16 * s + 8 * hi);
;                 acc[mt] = __builtin_amdgcn_mfma_f32_32x32x16_bf16(af, bf, acc[mt], 0, 0, 0); }
;         }
;         unsigned* zs = (unsigned*)(ws + WS_ZS);
; #pragma unroll
;         for (int mt = 0; mt < 4; ++mt)
; #pragma unroll
;             for (int rq = 0; rq < 4; ++rq)
; #pragma unroll
;                 for (int e = 0; e < 2; ++e) {
;                     const int k1 = 16 * mt + 4 * rq + 2 * hi + e; const int idx = k1 * l2;
;                     const float ct = TAB[TAB_COS + idx], st = TAB[TAB_COS + ((idx - 2048) & 8191)];
	v_mfma_f32_32x32x16_bf16 v[0:15], v[96:99], v[64:67], v[0:15]
	v_mfma_f32_32x32x16_bf16 v[16:31], v[100:103], v[64:67], v[16:31]
	v_mfma_f32_32x32x16_bf16 v[32:47], v[104:107], v[64:67], v[32:47]
	v_mfma_f32_32x32x16_bf16 v[48:63], v[108:111], v[64:67], v[48:63]
	s_waitcnt vmcnt(8)
	v_mfma_f32_32x32x16_bf16 v[0:15], v[112:115], v[68:71], v[0:15]
	v_mfma_f32_32x32x16_bf16 v[16:31], v[116:119], v[68:71], v[16:31]
	v_mfma_f32_32x32x16_bf16 v[32:47], v[120:123], v[68:71], v[32:47]
	v_mfma_f32_32x32x16_bf16 v[48:63], v[124:127], v[68:71], v[48:63]
	s_nop 1
	global_load_dwordx4 v[96:99], v171, s[2:3] offset:128
	global_load_dwordx4 v[100:103], v172, s[2:3] offset:128
	global_load_dwordx4 v[104:107], v173, s[2:3] offset:128
	global_load_dwordx4 v[108:111], v174, s[2:3] offset:128
	s_waitcnt vmcnt(8)
	v_mfma_f32_32x32x16_bf16 v[0:15], v[128:131], v[72:75], v[0:15]
	v_mfma_f32_32x32x16_bf16 v[16:31], v[132:135], v[72:75], v[16:31]
	v_mfma_f32_32x32x16_bf16 v[32:47], v[136:139], v[72:75], v[32:47]
	v_mfma_f32_32x32x16_bf16 v[48:63], v[140:143], v[72:75], v[48:63]
	s_nop 1
	global_load_dwordx4 v[112:115], v171, s[2:3] offset:160
	global_load_dwordx4 v[116:119], v172, s[2:3] offset:160
	global_load_dwordx4 v[120:123], v173, s[2:3] offset:160
	global_load_dwordx4 v[124:127], v174, s[2:3] offset:160
	s_waitcnt vmcnt(8)
	v_mfma_f32_32x32x16_bf16 v[0:15], v[148:151], v[76:79], v[0:15]
	v_mfma_f32_32x32x16_bf16 v[16:31], v[152:155], v[76:79], v[16:31]
	v_mfma_f32_32x32x16_bf16 v[32:47], v[156:159], v[76:79], v[32:47]
	v_mfma_f32_32x32x16_bf16 v[48:63], v[160:163], v[76:79], v[48:63]
	s_nop 1
	global_load_dwordx4 v[128:131], v171, s[2:3] offset:192
	global_load_dwordx4 v[132:135], v172, s[2:3] offset:192
	global_load_dwordx4 v[136:139], v173, s[2:3] offset:192
	global_load_dwordx4 v[140:143], v174, s[2:3] offset:192
	s_waitcnt vmcnt(8)
	v_mfma_f32_32x32x16_bf16 v[0:15], v[96:99], v[80:83], v[0:15]
	v_mfma_f32_32x32x16_bf16 v[16:31], v[100:103], v[80:83], v[16:31]
	v_mfma_f32_32x32x16_bf16 v[32:47], v[104:107], v[80:83], v[32:47]
	v_mfma_f32_32x32x16_bf16 v[48:63], v[108:111], v[80:83], v[48:63]
	s_nop 1
	global_load_dwordx4 v[148:151], v171, s[2:3] offset:224
	global_load_dwordx4 v[152:155], v172, s[2:3] offset:224
	global_load_dwordx4 v[156:159], v173, s[2:3] offset:224
	global_load_dwordx4 v[160:163], v174, s[2:3] offset:224
	s_waitcnt vmcnt(8)
	v_mfma_f32_32x32x16_bf16 v[0:15], v[112:115], v[84:87], v[0:15]
	v_mfma_f32_32x32x16_bf16 v[16:31], v[116:119], v[84:87], v[16:31]
	v_mfma_f32_32x32x16_bf16 v[32:47], v[120:123], v[84:87], v[32:47]
	v_mfma_f32_32x32x16_bf16 v[48:63], v[124:127], v[84:87], v[48:63]
	s_waitcnt vmcnt(4)
	v_mfma_f32_32x32x16_bf16 v[0:15], v[128:131], v[88:91], v[0:15]
	v_mfma_f32_32x32x16_bf16 v[16:31], v[132:135], v[88:91], v[16:31]
	v_mfma_f32_32x32x16_bf16 v[32:47], v[136:139], v[88:91], v[32:47]
	v_mfma_f32_32x32x16_bf16 v[48:63], v[140:143], v[88:91], v[48:63]
	s_waitcnt vmcnt(0)
	v_mfma_f32_32x32x16_bf16 v[0:15], v[148:151], v[92:95], v[0:15]
	v_mfma_f32_32x32x16_bf16 v[16:31], v[152:155], v[92:95], v[16:31]
	v_mfma_f32_32x32x16_bf16 v[32:47], v[156:159], v[92:95], v[32:47]
	v_mfma_f32_32x32x16_bf16 v[48:63], v[160:163], v[92:95], v[48:63]
	s_and_b32 s3, s26, 0x7f
	v_mul_u32_u24_e32 v177, s3, v176
	v_lshlrev_b32_e32 v177, 1, v177
	s_mul_i32 s2, s3, 0
	v_add_u32_e32 v178, s2, v177
	v_add_u32_e32 v179, 0xfffff800, v178
	v_lshlrev_b32_e32 v178, 2, v178
	v_and_b32_e32 v179, 0x1fff, v179
	v_lshlrev_b32_e32 v179, 2, v179
	global_load_dword v64, v178, s[6:7]
	global_load_dword v96, v179, s[6:7]
	s_mul_i32 s2, s3, 1
	v_add_u32_e32 v178, s2, v177
	v_add_u32_e32 v179, 0xfffff800, v178
	v_lshlrev_b32_e32 v178, 2, v178
	v_and_b32_e32 v179, 0x1fff, v179
	v_lshlrev_b32_e32 v179, 2, v179
	global_load_dword v65, v178, s[6:7]
	global_load_dword v97, v179, s[6:7]
	s_mul_i32 s2, s3, 4
	v_add_u32_e32 v178, s2, v177
	v_add_u32_e32 v179, 0xfffff800, v178
	v_lshlrev_b32_e32 v178, 2, v178
	v_and_b32_e32 v179, 0x1fff, v179
	v_lshlrev_b32_e32 v179, 2, v179
	global_load_dword v66, v178, s[6:7]
	global_load_dword v98, v179, s[6:7]
	s_mul_i32 s2, s3, 5
	v_add_u32_e32 v178, s2, v177
	v_add_u32_e32 v179, 0xfffff800, v178
	v_lshlrev_b32_e32 v178, 2, v178
	v_and_b32_e32 v179, 0x1fff, v179
	v_lshlrev_b32_e32 v179, 2, v179
	global_load_dword v67, v178, s[6:7]
	global_load_dword v99, v179, s[6:7]
	s_mul_i32 s2, s3, 8
	v_add_u32_e32 v178, s2, v177
	v_add_u32_e32 v179, 0xfffff800, v178
	v_lshlrev_b32_e32 v178, 2, v178
	v_and_b32_e32 v179, 0x1fff, v179
	v_lshlrev_b32_e32 v179, 2, v179
	global_load_dword v68, v178, s[6:7]
	global_load_dword v100, v179, s[6:7]
	s_mul_i32 s2, s3, 9
	v_add_u32_e32 v178, s2, v177
	v_add_u32_e32 v179, 0xfffff800, v178
	v_lshlrev_b32_e32 v178, 2, v178
	v_and_b32_e32 v179, 0x1fff, v179
	v_lshlrev_b32_e32 v179, 2, v179
	global_load_dword v69, v178, s[6:7]
	global_load_dword v101, v179, s[6:7]
	s_mul_i32 s2, s3, 12
	v_add_u32_e32 v178, s2, v177
	v_add_u32_e32 v179, 0xfffff800, v178
	v_lshlrev_b32_e32 v178, 2, v178
	v_and_b32_e32 v179, 0x1fff, v179
	v_lshlrev_b32_e32 v179, 2, v179
	global_load_dword v70, v178, s[6:7]
	global_load_dword v102, v179, s[6:7]
	s_mul_i32 s2, s3, 13
	v_add_u32_e32 v178, s2, v177
	v_add_u32_e32 v179, 0xfffff800, v178
	v_lshlrev_b32_e32 v178, 2, v178
	v_and_b32_e32 v179, 0x1fff, v179
	v_lshlrev_b32_e32 v179, 2, v179
	global_load_dword v71, v178, s[6:7]
	global_load_dword v103, v179, s[6:7]
	s_mul_i32 s2, s3, 16
	v_add_u32_e32 v178, s2, v177
	v_add_u32_e32 v179, 0xfffff800, v178
	v_lshlrev_b32_e32 v178, 2, v178
	v_and_b32_e32 v179, 0x1fff, v179
	v_lshlrev_b32_e32 v179, 2, v179
	global_load_dword v72, v178, s[6:7]
; __device__ __forceinline__ unsigned cvtpk(float lo, float hi) { const at_f32x2 v = {lo, hi}; const at_bf16x2 b = __builtin_convertvector(v, at_bf16x2); return __builtin_bit_cast(unsigned, b); }
; __device__ __forceinline__ void fft1_phase(KP P, int l) {
;     ...
; #pragma unroll
;         for (int mt = 0; mt < 4; ++mt)
; #pragma unroll
;             for (int rq = 0; rq < 4; ++rq)
; #pragma unroll
;                 for (int e = 0; e < 2; ++e) {
;                     const int k1 = 16 * mt + 4 * rq + 2 * hi + e; const int idx = k1 * l2;
;                     const float ct = TAB[TAB_COS + idx], st = TAB[TAB_COS + ((idx - 2048) & 8191)];
;                     const float yr = acc[mt][4 * rq + 2 * e], yi = acc[mt][4 * rq + 2 * e + 1];
;                     zs[((size_t)(b * 64 + k1) * 128 + l2) * 256 + ch] = cvtpk(yr * ct + yi * st, yi * ct - yr * st);
;                 }
	global_load_dword v104, v179, s[6:7]
	s_mul_i32 s2, s3, 17
	v_add_u32_e32 v178, s2, v177
	v_add_u32_e32 v179, 0xfffff800, v178
	v_lshlrev_b32_e32 v178, 2, v178
	v_and_b32_e32 v179, 0x1fff, v179
	v_lshlrev_b32_e32 v179, 2, v179
	global_load_dword v73, v178, s[6:7]
	global_load_dword v105, v179, s[6:7]
	s_mul_i32 s2, s3, 20
	v_add_u32_e32 v178, s2, v177
	v_add_u32_e32 v179, 0xfffff800, v178
	v_lshlrev_b32_e32 v178, 2, v178
	v_and_b32_e32 v179, 0x1fff, v179
	v_lshlrev_b32_e32 v179, 2, v179
	global_load_dword v74, v178, s[6:7]
	global_load_dword v106, v179, s[6:7]
	s_mul_i32 s2, s3, 21
	v_add_u32_e32 v178, s2, v177
	v_add_u32_e32 v179, 0xfffff800, v178
	v_lshlrev_b32_e32 v178, 2, v178
	v_and_b32_e32 v179, 0x1fff, v179
	v_lshlrev_b32_e32 v179, 2, v179
	global_load_dword v75, v178, s[6:7]
	global_load_dword v107, v179, s[6:7]
	s_mul_i32 s2, s3, 24
	v_add_u32_e32 v178, s2, v177
	v_add_u32_e32 v179, 0xfffff800, v178
	v_lshlrev_b32_e32 v178, 2, v178
	v_and_b32_e32 v179, 0x1fff, v179
	v_lshlrev_b32_e32 v179, 2, v179
	global_load_dword v76, v178, s[6:7]
	global_load_dword v108, v179, s[6:7]
	s_mul_i32 s2, s3, 25
	v_add_u32_e32 v178, s2, v177
	v_add_u32_e32 v179, 0xfffff800, v178
	v_lshlrev_b32_e32 v178, 2, v178
	v_and_b32_e32 v179, 0x1fff, v179
	v_lshlrev_b32_e32 v179, 2, v179
	global_load_dword v77, v178, s[6:7]
	global_load_dword v109, v179, s[6:7]
	s_mul_i32 s2, s3, 28
	v_add_u32_e32 v178, s2, v177
	v_add_u32_e32 v179, 0xfffff800, v178
	v_lshlrev_b32_e32 v178, 2, v178
	v_and_b32_e32 v179, 0x1fff, v179
	v_lshlrev_b32_e32 v179, 2, v179
	global_load_dword v78, v178, s[6:7]
	global_load_dword v110, v179, s[6:7]
	s_mul_i32 s2, s3, 29
	v_add_u32_e32 v178, s2, v177
	v_add_u32_e32 v179, 0xfffff800, v178
	v_lshlrev_b32_e32 v178, 2, v178
	v_and_b32_e32 v179, 0x1fff, v179
	v_lshlrev_b32_e32 v179, 2, v179
	global_load_dword v79, v178, s[6:7]
	global_load_dword v111, v179, s[6:7]
	s_lshr_b32 s2, s26, 7
	s_lshl_b32 s2, s2, 13
	s_add_u32 s2, s2, s3
	s_lshl_b32 s2, s2, 10
	s_add_u32 s2, s2, 0xa100000
	s_add_u32 s14, s12, s2
	s_addc_u32 s15, s13, 0
	s_waitcnt vmcnt(30)
	v_mul_f32_e32 v178, v1, v96
	v_mul_f32_e32 v179, v0, v96
	v_fma_f32 v178, v0, v64, v178
	v_fma_f32 v179, v1, v64, -v179
	v_cvt_pk_bf16_f32 v180, v178, v179
	global_store_dword v175, v180, s[14:15]
	s_add_u32 s14, s14, 0x20000
	s_addc_u32 s15, s15, 0
	s_waitcnt vmcnt(29)
	v_mul_f32_e32 v178, v3, v97
	v_mul_f32_e32 v179, v2, v97
	v_fma_f32 v178, v2, v65, v178
	v_fma_f32 v179, v3, v65, -v179
	v_cvt_pk_bf16_f32 v181, v178, v179
	global_store_dword v175, v181, s[14:15]
	s_add_u32 s14, s14, 0x60000
	s_addc_u32 s15, s15, 0
	s_waitcnt vmcnt(28)
	v_mul_f32_e32 v178, v5, v98
	v_mul_f32_e32 v179, v4, v98
	v_fma_f32 v178, v4, v66, v178
	v_fma_f32 v179, v5, v66, -v179
	v_cvt_pk_bf16_f32 v180, v178, v179
	global_store_dword v175, v180, s[14:15]
	s_add_u32 s14, s14, 0x20000
	s_addc_u32 s15, s15, 0
	s_waitcnt vmcnt(27)
	v_mul_f32_e32 v178, v7, v99
	v_mul_f32_e32 v179, v6, v99
	v_fma_f32 v178, v6, v67, v178
	v_fma_f32 v179, v7, v67, -v179
	v_cvt_pk_bf16_f32 v181, v178, v179
	global_store_dword v175, v181, s[14:15]
	s_add_u32 s14, s14, 0x60000
	s_addc_u32 s15, s15, 0
	s_waitcnt vmcnt(26)
	v_mul_f32_e32 v178, v9, v100
	v_mul_f32_e32 v179, v8, v100
	v_fma_f32 v178, v8, v68, v178
	v_fma_f32 v179, v9, v68, -v179
	v_cvt_pk_bf16_f32 v180, v178, v179
	global_store_dword v175, v180, s[14:15]
	s_add_u32 s14, s14, 0x20000
	s_addc_u32 s15, s15, 0
	s_waitcnt vmcnt(25)
	v_mul_f32_e32 v178, v11, v101
	v_mul_f32_e32 v179, v10, v101
	v_fma_f32 v178, v10, v69, v178
	v_fma_f32 v179, v11, v69, -v179
	v_cvt_pk_bf16_f32 v181, v178, v179
	global_store_dword v175, v181, s[14:15]
	s_add_u32 s14, s14, 0x60000
	s_addc_u32 s15, s15, 0
	s_waitcnt vmcnt(24)
	v_mul_f32_e32 v178, v13, v102
	v_mul_f32_e32 v179, v12, v102
	v_fma_f32 v178, v12, v70, v178
	v_fma_f32 v179, v13, v70, -v179
	v_cvt_pk_bf16_f32 v180, v178, v179
	global_store_dword v175, v180, s[14:15]
	s_add_u32 s14, s14, 0x20000
	s_addc_u32 s15, s15, 0
	s_waitcnt vmcnt(23)
	v_mul_f32_e32 v178, v15, v103
	v_mul_f32_e32 v179, v14, v103
	v_fma_f32 v178, v14, v71, v178
	v_fma_f32 v179, v15, v71, -v179
	v_cvt_pk_bf16_f32 v181, v178, v179
	global_store_dword v175, v181, s[14:15]
	s_add_u32 s14, s14, 0x60000
	s_addc_u32 s15, s15, 0
	s_waitcnt vmcnt(22)
	v_mul_f32_e32 v178, v17, v104
	v_mul_f32_e32 v179, v16, v104
	v_fma_f32 v178, v16, v72, v178
	v_fma_f32 v179, v17, v72, -v179
	v_cvt_pk_bf16_f32 v180, v178, v179
	global_store_dword v175, v180, s[14:15]
	s_add_u32 s14, s14, 0x20000
	s_addc_u32 s15, s15, 0
	s_waitcnt vmcnt(21)
	v_mul_f32_e32 v178, v19, v105
	v_mul_f32_e32 v179, v18, v105
	v_fma_f32 v178, v18, v73, v178
	v_fma_f32 v179, v19, v73, -v179
	v_cvt_pk_bf16_f32 v181, v178, v179
	global_store_dword v175, v181, s[14:15]
	s_add_u32 s14, s14, 0x60000
	s_addc_u32 s15, s15, 0
	s_waitcnt vmcnt(20)
	v_mul_f32_e32 v178, v21, v106
	v_mul_f32_e32 v179, v20, v106
	v_fma_f32 v178, v20, v74, v178
	v_fma_f32 v179, v21, v74, -v179
	v_cvt_pk_bf16_f32 v180, v178, v179
	global_store_dword v175, v180, s[14:15]
	s_add_u32 s14, s14, 0x20000
	s_addc_u32 s15, s15, 0
	s_waitcnt vmcnt(19)
	v_mul_f32_e32 v178, v23, v107
	v_mul_f32_e32 v179, v22, v107
	v_fma_f32 v178, v22, v75, v178
	v_fma_f32 v179, v23, v75, -v179
	v_cvt_pk_bf16_f32 v181, v178, v179
	global_store_dword v175, v181, s[14:15]
	s_add_u32 s14, s14, 0x60000
	s_addc_u32 s15, s15, 0
	s_waitcnt vmcnt(18)
	v_mul_f32_e32 v178, v25, v108
	v_mul_f32_e32 v179, v24, v108
	v_fma_f32 v178, v24, v76, v178
	v_fma_f32 v179, v25, v76, -v179
	v_cvt_pk_bf16_f32 v180, v178, v179
	global_store_dword v175, v180, s[14:15]
	s_add_u32 s14, s14, 0x20000
	s_addc_u32 s15, s15, 0
	s_waitcnt vmcnt(17)
; __device__ __forceinline__ unsigned cvtpk(float lo, float hi) { const at_f32x2 v = {lo, hi}; const at_bf16x2 b = __builtin_convertvector(v, at_bf16x2); return __builtin_bit_cast(unsigned, b); }
; __device__ __forceinline__ void fft1_phase(KP P, int l) {
;     ...
; #pragma unroll
;         for (int mt = 0; mt < 4; ++mt)
; #pragma unroll
;             for (int rq = 0; rq < 4; ++rq)
; #pragma unroll
;                 for (int e = 0; e < 2; ++e) {
;                     const int k1 = 16 * mt + 4 * rq + 2 * hi + e; const int idx = k1 * l2;
;                     const float ct = TAB[TAB_COS + idx], st = TAB[TAB_COS + ((idx - 2048) & 8191)];
;                     const float yr = acc[mt][4 * rq + 2 * e], yi = acc[mt][4 * rq + 2 * e + 1];
;                     zs[((size_t)(b * 64 + k1) * 128 + l2) * 256 + ch] = cvtpk(yr * ct + yi * st, yi * ct - yr * st);
;                 }
	v_mul_f32_e32 v178, v27, v109
	v_mul_f32_e32 v179, v26, v109
	v_fma_f32 v178, v26, v77, v178
	v_fma_f32 v179, v27, v77, -v179
	v_cvt_pk_bf16_f32 v181, v178, v179
	global_store_dword v175, v181, s[14:15]
	s_add_u32 s14, s14, 0x60000
	s_addc_u32 s15, s15, 0
	s_waitcnt vmcnt(16)
	v_mul_f32_e32 v178, v29, v110
	v_mul_f32_e32 v179, v28, v110
	v_fma_f32 v178, v28, v78, v178
	v_fma_f32 v179, v29, v78, -v179
	v_cvt_pk_bf16_f32 v180, v178, v179
	global_store_dword v175, v180, s[14:15]
	s_add_u32 s14, s14, 0x20000
	s_addc_u32 s15, s15, 0
	s_waitcnt vmcnt(15)
	v_mul_f32_e32 v178, v31, v111
	v_mul_f32_e32 v179, v30, v111
	v_fma_f32 v178, v30, v79, v178
	v_fma_f32 v179, v31, v79, -v179
	v_cvt_pk_bf16_f32 v181, v178, v179
	global_store_dword v175, v181, s[14:15]
	s_waitcnt vmcnt(0)
	s_mul_i32 s2, s3, 32
	v_add_u32_e32 v178, s2, v177
	v_add_u32_e32 v179, 0xfffff800, v178
	v_lshlrev_b32_e32 v178, 2, v178
	v_and_b32_e32 v179, 0x1fff, v179
	v_lshlrev_b32_e32 v179, 2, v179
	global_load_dword v80, v178, s[6:7]
	global_load_dword v112, v179, s[6:7]
	s_mul_i32 s2, s3, 33
	v_add_u32_e32 v178, s2, v177
	v_add_u32_e32 v179, 0xfffff800, v178
	v_lshlrev_b32_e32 v178, 2, v178
	v_and_b32_e32 v179, 0x1fff, v179
	v_lshlrev_b32_e32 v179, 2, v179
	global_load_dword v81, v178, s[6:7]
	global_load_dword v113, v179, s[6:7]
	s_mul_i32 s2, s3, 36
	v_add_u32_e32 v178, s2, v177
	v_add_u32_e32 v179, 0xfffff800, v178
	v_lshlrev_b32_e32 v178, 2, v178
	v_and_b32_e32 v179, 0x1fff, v179
	v_lshlrev_b32_e32 v179, 2, v179
	global_load_dword v82, v178, s[6:7]
	global_load_dword v114, v179, s[6:7]
	s_mul_i32 s2, s3, 37
	v_add_u32_e32 v178, s2, v177
	v_add_u32_e32 v179, 0xfffff800, v178
	v_lshlrev_b32_e32 v178, 2, v178
	v_and_b32_e32 v179, 0x1fff, v179
	v_lshlrev_b32_e32 v179, 2, v179
	global_load_dword v83, v178, s[6:7]
	global_load_dword v115, v179, s[6:7]
	s_mul_i32 s2, s3, 40
	v_add_u32_e32 v178, s2, v177
	v_add_u32_e32 v179, 0xfffff800, v178
	v_lshlrev_b32_e32 v178, 2, v178
	v_and_b32_e32 v179, 0x1fff, v179
	v_lshlrev_b32_e32 v179, 2, v179
	global_load_dword v84, v178, s[6:7]
	global_load_dword v116, v179, s[6:7]
	s_mul_i32 s2, s3, 41
	v_add_u32_e32 v178, s2, v177
	v_add_u32_e32 v179, 0xfffff800, v178
	v_lshlrev_b32_e32 v178, 2, v178
	v_and_b32_e32 v179, 0x1fff, v179
	v_lshlrev_b32_e32 v179, 2, v179
	global_load_dword v85, v178, s[6:7]
	global_load_dword v117, v179, s[6:7]
	s_mul_i32 s2, s3, 44
	v_add_u32_e32 v178, s2, v177
	v_add_u32_e32 v179, 0xfffff800, v178
	v_lshlrev_b32_e32 v178, 2, v178
	v_and_b32_e32 v179, 0x1fff, v179
	v_lshlrev_b32_e32 v179, 2, v179
	global_load_dword v86, v178, s[6:7]
	global_load_dword v118, v179, s[6:7]
	s_mul_i32 s2, s3, 45
	v_add_u32_e32 v178, s2, v177
	v_add_u32_e32 v179, 0xfffff800, v178
	v_lshlrev_b32_e32 v178, 2, v178
	v_and_b32_e32 v179, 0x1fff, v179
	v_lshlrev_b32_e32 v179, 2, v179
	global_load_dword v87, v178, s[6:7]
	global_load_dword v119, v179, s[6:7]
	s_mul_i32 s2, s3, 48
	v_add_u32_e32 v178, s2, v177
	v_add_u32_e32 v179, 0xfffff800, v178
	v_lshlrev_b32_e32 v178, 2, v178
	v_and_b32_e32 v179, 0x1fff, v179
	v_lshlrev_b32_e32 v179, 2, v179
	global_load_dword v88, v178, s[6:7]
	global_load_dword v120, v179, s[6:7]
	s_mul_i32 s2, s3, 49
	v_add_u32_e32 v178, s2, v177
	v_add_u32_e32 v179, 0xfffff800, v178
	v_lshlrev_b32_e32 v178, 2, v178
	v_and_b32_e32 v179, 0x1fff, v179
	v_lshlrev_b32_e32 v179, 2, v179
	global_load_dword v89, v178, s[6:7]
	global_load_dword v121, v179, s[6:7]
	s_mul_i32 s2, s3, 52
	v_add_u32_e32 v178, s2, v177
	v_add_u32_e32 v179, 0xfffff800, v178
	v_lshlrev_b32_e32 v178, 2, v178
	v_and_b32_e32 v179, 0x1fff, v179
	v_lshlrev_b32_e32 v179, 2, v179
	global_load_dword v90, v178, s[6:7]
	global_load_dword v122, v179, s[6:7]
	s_mul_i32 s2, s3, 53
	v_add_u32_e32 v178, s2, v177
	v_add_u32_e32 v179, 0xfffff800, v178
	v_lshlrev_b32_e32 v178, 2, v178
	v_and_b32_e32 v179, 0x1fff, v179
	v_lshlrev_b32_e32 v179, 2, v179
	global_load_dword v91, v178, s[6:7]
	global_load_dword v123, v179, s[6:7]
	s_mul_i32 s2, s3, 56
	v_add_u32_e32 v178, s2, v177
	v_add_u32_e32 v179, 0xfffff800, v178
	v_lshlrev_b32_e32 v178, 2, v178
	v_and_b32_e32 v179, 0x1fff, v179
	v_lshlrev_b32_e32 v179, 2, v179
	global_load_dword v92, v178, s[6:7]
	global_load_dword v124, v179, s[6:7]
	s_mul_i32 s2, s3, 57
	v_add_u32_e32 v178, s2, v177
	v_add_u32_e32 v179, 0xfffff800, v178
	v_lshlrev_b32_e32 v178, 2, v178
	v_and_b32_e32 v179, 0x1fff, v179
	v_lshlrev_b32_e32 v179, 2, v179
	global_load_dword v93, v178, s[6:7]
	global_load_dword v125, v179, s[6:7]
	s_mul_i32 s2, s3, 60
	v_add_u32_e32 v178, s2, v177
	v_add_u32_e32 v179, 0xfffff800, v178
	v_lshlrev_b32_e32 v178, 2, v178
	v_and_b32_e32 v179, 0x1fff, v179
	v_lshlrev_b32_e32 v179, 2, v179
	global_load_dword v94, v178, s[6:7]
	global_load_dword v126, v179, s[6:7]
	s_mul_i32 s2, s3, 61
	v_add_u32_e32 v178, s2, v177
	v_add_u32_e32 v179, 0xfffff800, v178
	v_lshlrev_b32_e32 v178, 2, v178
	v_and_b32_e32 v179, 0x1fff, v179
	v_lshlrev_b32_e32 v179, 2, v179
	global_load_dword v95, v178, s[6:7]
	global_load_dword v127, v179, s[6:7]
	s_add_u32 s14, s14, 0x60000
	s_addc_u32 s15, s15, 0
	s_waitcnt vmcnt(30)
; __device__ __forceinline__ unsigned cvtpk(float lo, float hi) { const at_f32x2 v = {lo, hi}; const at_bf16x2 b = __builtin_convertvector(v, at_bf16x2); return __builtin_bit_cast(unsigned, b); }
; __device__ __forceinline__ void fft1_phase(KP P, int l) {
;     ...
;     for (int it = bid_; it < 256; it += gridDim.x) {
;     ...
; #pragma unroll
;         for (int mt = 0; mt < 4; ++mt)
; #pragma unroll
;             for (int rq = 0; rq < 4; ++rq)
; #pragma unroll
;                 for (int e = 0; e < 2; ++e) {
;                     const int k1 = 16 * mt + 4 * rq + 2 * hi + e; const int idx = k1 * l2;
;                     const float ct = TAB[TAB_COS + idx], st = TAB[TAB_COS + ((idx - 2048) & 8191)];
;                     const float yr = acc[mt][4 * rq + 2 * e], yi = acc[mt][4 * rq + 2 * e + 1];
;                     zs[((size_t)(b * 64 + k1) * 128 + l2) * 256 + ch] = cvtpk(yr * ct + yi * st, yi * ct - yr * st);
;                 }
	v_mul_f32_e32 v178, v33, v112
	v_mul_f32_e32 v179, v32, v112
	v_fma_f32 v178, v32, v80, v178
	v_fma_f32 v179, v33, v80, -v179
	v_cvt_pk_bf16_f32 v180, v178, v179
	global_store_dword v175, v180, s[14:15]
	s_add_u32 s14, s14, 0x20000
	s_addc_u32 s15, s15, 0
	s_waitcnt vmcnt(29)
	v_mul_f32_e32 v178, v35, v113
	v_mul_f32_e32 v179, v34, v113
	v_fma_f32 v178, v34, v81, v178
	v_fma_f32 v179, v35, v81, -v179
	v_cvt_pk_bf16_f32 v181, v178, v179
	global_store_dword v175, v181, s[14:15]
	s_add_u32 s14, s14, 0x60000
	s_addc_u32 s15, s15, 0
	s_waitcnt vmcnt(28)
	v_mul_f32_e32 v178, v37, v114
	v_mul_f32_e32 v179, v36, v114
	v_fma_f32 v178, v36, v82, v178
	v_fma_f32 v179, v37, v82, -v179
	v_cvt_pk_bf16_f32 v180, v178, v179
	global_store_dword v175, v180, s[14:15]
	s_add_u32 s14, s14, 0x20000
	s_addc_u32 s15, s15, 0
	s_waitcnt vmcnt(27)
	v_mul_f32_e32 v178, v39, v115
	v_mul_f32_e32 v179, v38, v115
	v_fma_f32 v178, v38, v83, v178
	v_fma_f32 v179, v39, v83, -v179
	v_cvt_pk_bf16_f32 v181, v178, v179
	global_store_dword v175, v181, s[14:15]
	s_add_u32 s14, s14, 0x60000
	s_addc_u32 s15, s15, 0
	s_waitcnt vmcnt(26)
	v_mul_f32_e32 v178, v41, v116
	v_mul_f32_e32 v179, v40, v116
	v_fma_f32 v178, v40, v84, v178
	v_fma_f32 v179, v41, v84, -v179
	v_cvt_pk_bf16_f32 v180, v178, v179
	global_store_dword v175, v180, s[14:15]
	s_add_u32 s14, s14, 0x20000
	s_addc_u32 s15, s15, 0
	s_waitcnt vmcnt(25)
	v_mul_f32_e32 v178, v43, v117
	v_mul_f32_e32 v179, v42, v117
	v_fma_f32 v178, v42, v85, v178
	v_fma_f32 v179, v43, v85, -v179
	v_cvt_pk_bf16_f32 v181, v178, v179
	global_store_dword v175, v181, s[14:15]
	s_add_u32 s14, s14, 0x60000
	s_addc_u32 s15, s15, 0
	s_waitcnt vmcnt(24)
	v_mul_f32_e32 v178, v45, v118
	v_mul_f32_e32 v179, v44, v118
	v_fma_f32 v178, v44, v86, v178
	v_fma_f32 v179, v45, v86, -v179
	v_cvt_pk_bf16_f32 v180, v178, v179
	global_store_dword v175, v180, s[14:15]
	s_add_u32 s14, s14, 0x20000
	s_addc_u32 s15, s15, 0
	s_waitcnt vmcnt(23)
	v_mul_f32_e32 v178, v47, v119
	v_mul_f32_e32 v179, v46, v119
	v_fma_f32 v178, v46, v87, v178
	v_fma_f32 v179, v47, v87, -v179
	v_cvt_pk_bf16_f32 v181, v178, v179
	global_store_dword v175, v181, s[14:15]
	s_add_u32 s14, s14, 0x60000
	s_addc_u32 s15, s15, 0
	s_waitcnt vmcnt(22)
	v_mul_f32_e32 v178, v49, v120
	v_mul_f32_e32 v179, v48, v120
	v_fma_f32 v178, v48, v88, v178
	v_fma_f32 v179, v49, v88, -v179
	v_cvt_pk_bf16_f32 v180, v178, v179
	global_store_dword v175, v180, s[14:15]
	s_add_u32 s14, s14, 0x20000
	s_addc_u32 s15, s15, 0
	s_waitcnt vmcnt(21)
	v_mul_f32_e32 v178, v51, v121
	v_mul_f32_e32 v179, v50, v121
	v_fma_f32 v178, v50, v89, v178
	v_fma_f32 v179, v51, v89, -v179
	v_cvt_pk_bf16_f32 v181, v178, v179
	global_store_dword v175, v181, s[14:15]
	s_add_u32 s14, s14, 0x60000
	s_addc_u32 s15, s15, 0
	s_waitcnt vmcnt(20)
	v_mul_f32_e32 v178, v53, v122
	v_mul_f32_e32 v179, v52, v122
	v_fma_f32 v178, v52, v90, v178
	v_fma_f32 v179, v53, v90, -v179
	v_cvt_pk_bf16_f32 v180, v178, v179
	global_store_dword v175, v180, s[14:15]
	s_add_u32 s14, s14, 0x20000
	s_addc_u32 s15, s15, 0
	s_waitcnt vmcnt(19)
	v_mul_f32_e32 v178, v55, v123
	v_mul_f32_e32 v179, v54, v123
	v_fma_f32 v178, v54, v91, v178
	v_fma_f32 v179, v55, v91, -v179
	v_cvt_pk_bf16_f32 v181, v178, v179
	global_store_dword v175, v181, s[14:15]
	s_add_u32 s14, s14, 0x60000
	s_addc_u32 s15, s15, 0
	s_waitcnt vmcnt(18)
	v_mul_f32_e32 v178, v57, v124
	v_mul_f32_e32 v179, v56, v124
	v_fma_f32 v178, v56, v92, v178
	v_fma_f32 v179, v57, v92, -v179
	v_cvt_pk_bf16_f32 v180, v178, v179
	global_store_dword v175, v180, s[14:15]
	s_add_u32 s14, s14, 0x20000
	s_addc_u32 s15, s15, 0
	s_waitcnt vmcnt(17)
	v_mul_f32_e32 v178, v59, v125
	v_mul_f32_e32 v179, v58, v125
	v_fma_f32 v178, v58, v93, v178
	v_fma_f32 v179, v59, v93, -v179
	v_cvt_pk_bf16_f32 v181, v178, v179
	global_store_dword v175, v181, s[14:15]
	s_add_u32 s14, s14, 0x60000
	s_addc_u32 s15, s15, 0
	s_waitcnt vmcnt(16)
	v_mul_f32_e32 v178, v61, v126
	v_mul_f32_e32 v179, v60, v126
	v_fma_f32 v178, v60, v94, v178
	v_fma_f32 v179, v61, v94, -v179
	v_cvt_pk_bf16_f32 v180, v178, v179
	global_store_dword v175, v180, s[14:15]
	s_add_u32 s14, s14, 0x20000
	s_addc_u32 s15, s15, 0
	s_waitcnt vmcnt(15)
	v_mul_f32_e32 v178, v63, v127
	v_mul_f32_e32 v179, v62, v127
	v_fma_f32 v178, v62, v95, v178
	v_fma_f32 v179, v63, v95, -v179
	v_cvt_pk_bf16_f32 v181, v178, v179
	global_store_dword v175, v181, s[14:15]
	s_load_dword s2, s[72:73], 0x0
	s_waitcnt lgkmcnt(0)
	s_add_i32 s26, s26, s2
	s_branch .Lf1_item
.Lf1_done:
.LBB0_43:
	s_add_i32 s2, s70, 10
	s_cmp_lt_u32 s2, 23
	s_movk_i32 s2, 0x600
	s_cbranch_scc0 .LBB0_50
	v_lshl_add_u32 v8, s0, 9, v146
	v_cmp_gt_i32_e32 vcc, s97, v8
	s_and_saveexec_b64 s[12:13], vcc
	s_cbranch_execz .LBB0_49
	v_readlane_b32 s2, v254, 18
	v_readlane_b32 s3, v254, 19
	s_load_dwordx2 s[14:15], s[2:3], 0xb8
	s_load_dword s0, s[72:73], 0x0
	v_lshlrev_b32_sdwa v168, v222, v146 dst_sel:DWORD dst_unused:UNUSED_PAD src0_sel:DWORD src1_sel:BYTE_0
	v_mov_b32_e32 v2, 2
	s_mov_b64 s[2:3], 0x4200600
	s_waitcnt lgkmcnt(0)
	v_lshl_add_u64 v[0:1], s[14:15], 0, v[168:169]
	v_lshlrev_b32_sdwa v168, v2, v146 dst_sel:DWORD dst_unused:UNUSED_PAD src0_sel:DWORD src1_sel:BYTE_0
	v_lshl_add_u64 v[0:1], v[0:1], 0, s[2:3]
	s_lshl_b32 s0, s0, 9
	v_lshl_add_u64 v[2:3], s[14:15], 0, v[168:169]
	s_mov_b64 s[14:15], 0

;     __device__ __forceinline__ void operator()(const f32x4 (&acc)[2][2][4][2], const Unit& u, int wr, int wc, int fr, int fq) const {
;         const float* gate = MODl + tile_w(u.pm) * NMOD + gate_chunk * 1024;
;         const bool part = u.ko != 0;
;         float* base = part ? PART + ((size_t)((u.ko >> 8) - 1) * 512 + (u.pm == 32 ? 0 : 256) + wr * 64 + fr) * DM : H + (size_t)(u.pm * BM + wr * 64 + fr) * DM;
; #pragma unroll
;         for (int bj = 0; bj < 2; ++bj)
; #pragma unroll
;             for (int n = 0; n < 2; ++n) {
;                 const int col = u.pn * BM + bj * HALF + wc * 32 + n * 16 + fq * 4;
;                 const f32x4 gv = *(const f32x4*)(gate + col) * coef;
;                 f32x4 old[2][4];
; #pragma unroll
;                 for (int ai = 0; ai < 2; ++ai)
; #pragma unroll
;                     for (int m = 0; m < 4; ++m) old[ai][m] = part ? (f32x4){0.f, 0.f, 0.f, 0.f} : *(const f32x4*)(base + (size_t)(ai * HALF + m * 16) * DM + col);
; #pragma unroll
;                 for (int ai = 0; ai < 2; ++ai)
; #pragma unroll
;                     for (int m = 0; m < 4; ++m) *(f32x4*)(base + (size_t)(ai * HALF + m * 16) * DM + col) = old[ai][m] + gv * acc[ai][bj][m][n];
;             }
.LBB0_276:
	s_lshr_b32 s8, s53, 31
	s_ashr_i32 s9, s53, 3
	s_add_i32 s8, s9, s8
	s_mul_i32 s9, s8, 0xffffffdf
	s_add_i32 s9, s9, s79
	s_mulk_i32 s8, 0x2400
	s_cmp_lg_u32 s9, 32
	s_cselect_b32 s8, s8, 0x4800
	s_ashr_i32 s9, s8, 31
	s_waitcnt vmcnt(0)
	v_or_b32_e32 v130, s23, v180
	s_lshl_b64 s[8:9], s[8:9], 2
	v_lshl_or_b32 v130, s61, 8, v130
	s_add_u32 s8, s71, s8
	v_ashrrev_i32_e32 v131, 31, v130
	s_addc_u32 s9, s65, s9
	v_lshlrev_b64 v[130:131], 2, v[130:131]
	v_lshl_add_u64 v[210:211], s[8:9], 0, v[130:131]
	s_and_b64 vcc, exec, s[10:11]
	s_cbranch_vccz .Ler_orig
	v_lshl_add_u64 v[212:213], v[128:129], 0, v[130:131]
	global_load_dwordx4 v[128:131], v[210:211], off offset:0
	global_load_dwordx4 v[132:135], v[210:211], off offset:64
	global_load_dwordx4 v[136:139], v[210:211], off offset:512
	global_load_dwordx4 v[140:143], v[210:211], off offset:576
	s_mov_b32 s13, 0
	s_mov_b32 s12, 0x10000
	v_lshl_add_u64 v[246:247], v[212:213], 0, s[12:13]
	s_mov_b32 s12, 0x20000
	v_lshl_add_u64 v[248:249], v[212:213], 0, s[12:13]
	s_mov_b32 s12, 0x30000
	v_lshl_add_u64 v[250:251], v[212:213], 0, s[12:13]
	s_mov_b32 s12, 0x80000
	v_lshl_add_u64 v[252:253], v[212:213], 0, s[12:13]
	s_mov_b32 s12, 0x90000
	v_lshl_add_u64 v[218:219], v[212:213], 0, s[12:13]
	s_mov_b32 s12, 0xa0000
	v_lshl_add_u64 v[220:221], v[212:213], 0, s[12:13]
	s_mov_b32 s12, 0xb0000
	v_lshl_add_u64 v[214:215], v[212:213], 0, s[12:13]
	global_load_dwordx4 v[144:147], v[212:213], off offset:0
	global_load_dwordx4 v[148:151], v[212:213], off offset:64
	global_load_dwordx4 v[152:155], v[212:213], off offset:512
	global_load_dwordx4 v[156:159], v[212:213], off offset:576
	global_load_dwordx4 v[160:163], v[246:247], off offset:0
	global_load_dwordx4 v[234:237], v[246:247], off offset:64
	global_load_dwordx4 v[238:241], v[246:247], off offset:512
	global_load_dwordx4 v[242:245], v[246:247], off offset:576
	v_mov_b32_e32 v171, v170
	s_waitcnt vmcnt(8)
	v_pk_mul_f32 v[130:131], v[170:171], v[130:131]
	v_pk_mul_f32 v[128:129], v[172:173], v[128:129]
	v_pk_mul_f32 v[134:135], v[170:171], v[134:135]
	v_pk_mul_f32 v[132:133], v[172:173], v[132:133]
	v_pk_mul_f32 v[138:139], v[170:171], v[138:139]
	v_pk_mul_f32 v[136:137], v[172:173], v[136:137]
	v_pk_mul_f32 v[142:143], v[170:171], v[142:143]
	v_pk_mul_f32 v[140:141], v[172:173], v[140:141]
	s_waitcnt vmcnt(7)
	v_pk_fma_f32 v[146:147], v[126:127], v[130:131], v[146:147]
	v_pk_fma_f32 v[144:145], v[124:125], v[128:129], v[144:145]
	global_store_dwordx4 v[212:213], v[144:147], off offset:0
	s_nop 0
	global_load_dwordx4 v[144:147], v[248:249], off offset:0
	s_waitcnt vmcnt(8)
	v_pk_fma_f32 v[150:151], v[118:119], v[134:135], v[150:151]
	v_pk_fma_f32 v[148:149], v[116:117], v[132:133], v[148:149]
	global_store_dwordx4 v[212:213], v[148:151], off offset:64
	s_nop 0
	global_load_dwordx4 v[148:151], v[248:249], off offset:64
	s_waitcnt vmcnt(9)
	v_pk_fma_f32 v[154:155], v[122:123], v[138:139], v[154:155]
	v_pk_fma_f32 v[152:153], v[120:121], v[136:137], v[152:153]
	global_store_dwordx4 v[212:213], v[152:155], off offset:512
	s_nop 0
	global_load_dwordx4 v[152:155], v[248:249], off offset:512
	s_waitcnt vmcnt(10)
	v_pk_fma_f32 v[158:159], v[114:115], v[142:143], v[158:159]
	v_pk_fma_f32 v[156:157], v[112:113], v[140:141], v[156:157]
	global_store_dwordx4 v[212:213], v[156:159], off offset:576
	s_nop 0
	global_load_dwordx4 v[156:159], v[248:249], off offset:576
	s_waitcnt vmcnt(11)
	v_pk_fma_f32 v[162:163], v[110:111], v[130:131], v[162:163]
	v_pk_fma_f32 v[160:161], v[108:109], v[128:129], v[160:161]
	global_store_dwordx4 v[246:247], v[160:163], off offset:0
	s_nop 0
	global_load_dwordx4 v[160:163], v[250:251], off offset:0
	s_waitcnt vmcnt(12)
	v_pk_fma_f32 v[236:237], v[102:103], v[134:135], v[236:237]
	v_pk_fma_f32 v[234:235], v[100:101], v[132:133], v[234:235]
	global_store_dwordx4 v[246:247], v[234:237], off offset:64
	s_nop 0
	global_load_dwordx4 v[234:237], v[250:251], off offset:64
	s_waitcnt vmcnt(13)
	v_pk_fma_f32 v[240:241], v[106:107], v[138:139], v[240:241]
	v_pk_fma_f32 v[238:239], v[104:105], v[136:137], v[238:239]
	global_store_dwordx4 v[246:247], v[238:241], off offset:512
	s_nop 0
	global_load_dwordx4 v[238:241], v[250:251], off offset:512
	s_waitcnt vmcnt(14)
	v_pk_fma_f32 v[244:245], v[98:99], v[142:143], v[244:245]
	v_pk_fma_f32 v[242:243], v[96:97], v[140:141], v[242:243]
	global_store_dwordx4 v[246:247], v[242:245], off offset:576
	s_nop 0
	global_load_dwordx4 v[242:245], v[250:251], off offset:576
	s_waitcnt vmcnt(14)
	v_pk_fma_f32 v[146:147], v[94:95], v[130:131], v[146:147]
	v_pk_fma_f32 v[144:145], v[92:93], v[128:129], v[144:145]
	global_store_dwordx4 v[248:249], v[144:147], off offset:0
	s_nop 0
	global_load_dwordx4 v[144:147], v[252:253], off offset:0
	s_waitcnt vmcnt(14)
	v_pk_fma_f32 v[150:151], v[86:87], v[134:135], v[150:151]
	v_pk_fma_f32 v[148:149], v[84:85], v[132:133], v[148:149]
	global_store_dwordx4 v[248:249], v[148:151], off offset:64
	s_nop 0
	global_load_dwordx4 v[148:151], v[252:253], off offset:64
	s_waitcnt vmcnt(14)
	v_pk_fma_f32 v[154:155], v[90:91], v[138:139], v[154:155]
	v_pk_fma_f32 v[152:153], v[88:89], v[136:137], v[152:153]
	global_store_dwordx4 v[248:249], v[152:155], off offset:512
	s_nop 0
	global_load_dwordx4 v[152:155], v[252:253], off offset:512
	s_waitcnt vmcnt(14)
;     __device__ __forceinline__ void operator()(const f32x4 (&acc)[2][2][4][2], const Unit& u, int wr, int wc, int fr, int fq) const {
;     ...
;             for (int n = 0; n < 2; ++n) {
;                 const int col = u.pn * BM + bj * HALF + wc * 32 + n * 16 + fq * 4;
;                 const f32x4 gv = *(const f32x4*)(gate + col) * coef;
;                 f32x4 old[2][4];
; #pragma unroll
;                 for (int ai = 0; ai < 2; ++ai)
; #pragma unroll
;                     for (int m = 0; m < 4; ++m) old[ai][m] = part ? (f32x4){0.f, 0.f, 0.f, 0.f} : *(const f32x4*)(base + (size_t)(ai * HALF + m * 16) * DM + col);
; #pragma unroll
;                 for (int ai = 0; ai < 2; ++ai)
; #pragma unroll
;                     for (int m = 0; m < 4; ++m) *(f32x4*)(base + (size_t)(ai * HALF + m * 16) * DM + col) = old[ai][m] + gv * acc[ai][bj][m][n];
;             }
	v_pk_fma_f32 v[158:159], v[82:83], v[142:143], v[158:159]
	v_pk_fma_f32 v[156:157], v[80:81], v[140:141], v[156:157]
	global_store_dwordx4 v[248:249], v[156:159], off offset:576
	s_nop 0
	global_load_dwordx4 v[156:159], v[252:253], off offset:576
	s_waitcnt vmcnt(14)
	v_pk_fma_f32 v[162:163], v[78:79], v[130:131], v[162:163]
	v_pk_fma_f32 v[160:161], v[76:77], v[128:129], v[160:161]
	global_store_dwordx4 v[250:251], v[160:163], off offset:0
	s_nop 0
	global_load_dwordx4 v[160:163], v[218:219], off offset:0
	s_waitcnt vmcnt(14)
	v_pk_fma_f32 v[236:237], v[70:71], v[134:135], v[236:237]
	v_pk_fma_f32 v[234:235], v[68:69], v[132:133], v[234:235]
	global_store_dwordx4 v[250:251], v[234:237], off offset:64
	s_nop 0
	global_load_dwordx4 v[234:237], v[218:219], off offset:64
	s_waitcnt vmcnt(14)
	v_pk_fma_f32 v[240:241], v[74:75], v[138:139], v[240:241]
	v_pk_fma_f32 v[238:239], v[72:73], v[136:137], v[238:239]
	global_store_dwordx4 v[250:251], v[238:241], off offset:512
	s_nop 0
	global_load_dwordx4 v[238:241], v[218:219], off offset:512
	s_waitcnt vmcnt(14)
	v_pk_fma_f32 v[244:245], v[66:67], v[142:143], v[244:245]
	v_pk_fma_f32 v[242:243], v[64:65], v[140:141], v[242:243]
	global_store_dwordx4 v[250:251], v[242:245], off offset:576
	s_nop 0
	global_load_dwordx4 v[242:245], v[218:219], off offset:576
	s_waitcnt vmcnt(14)
	v_pk_fma_f32 v[146:147], v[62:63], v[130:131], v[146:147]
	v_pk_fma_f32 v[144:145], v[60:61], v[128:129], v[144:145]
	global_store_dwordx4 v[252:253], v[144:147], off offset:0
	s_nop 0
	global_load_dwordx4 v[144:147], v[220:221], off offset:0
	s_waitcnt vmcnt(14)
	v_pk_fma_f32 v[150:151], v[54:55], v[134:135], v[150:151]
	v_pk_fma_f32 v[148:149], v[52:53], v[132:133], v[148:149]
	global_store_dwordx4 v[252:253], v[148:151], off offset:64
	s_nop 0
	global_load_dwordx4 v[148:151], v[220:221], off offset:64
	s_waitcnt vmcnt(14)
	v_pk_fma_f32 v[154:155], v[58:59], v[138:139], v[154:155]
	v_pk_fma_f32 v[152:153], v[56:57], v[136:137], v[152:153]
	global_store_dwordx4 v[252:253], v[152:155], off offset:512
	s_nop 0
	global_load_dwordx4 v[152:155], v[220:221], off offset:512
	s_waitcnt vmcnt(14)
	v_pk_fma_f32 v[158:159], v[50:51], v[142:143], v[158:159]
	v_pk_fma_f32 v[156:157], v[48:49], v[140:141], v[156:157]
	global_store_dwordx4 v[252:253], v[156:159], off offset:576
	s_nop 0
	global_load_dwordx4 v[156:159], v[220:221], off offset:576
	s_waitcnt vmcnt(14)
	v_pk_fma_f32 v[162:163], v[46:47], v[130:131], v[162:163]
	v_pk_fma_f32 v[160:161], v[44:45], v[128:129], v[160:161]
	global_store_dwordx4 v[218:219], v[160:163], off offset:0
	s_nop 0
	global_load_dwordx4 v[160:163], v[214:215], off offset:0
	s_waitcnt vmcnt(14)
	v_pk_fma_f32 v[236:237], v[38:39], v[134:135], v[236:237]
	v_pk_fma_f32 v[234:235], v[36:37], v[132:133], v[234:235]
	global_store_dwordx4 v[218:219], v[234:237], off offset:64
	s_nop 0
	global_load_dwordx4 v[234:237], v[214:215], off offset:64
	s_waitcnt vmcnt(14)
	v_pk_fma_f32 v[240:241], v[42:43], v[138:139], v[240:241]
	v_pk_fma_f32 v[238:239], v[40:41], v[136:137], v[238:239]
	global_store_dwordx4 v[218:219], v[238:241], off offset:512
	s_nop 0
	global_load_dwordx4 v[238:241], v[214:215], off offset:512
	s_waitcnt vmcnt(14)
	v_pk_fma_f32 v[244:245], v[34:35], v[142:143], v[244:245]
	v_pk_fma_f32 v[242:243], v[32:33], v[140:141], v[242:243]
	global_store_dwordx4 v[218:219], v[242:245], off offset:576
	s_nop 0
	global_load_dwordx4 v[242:245], v[214:215], off offset:576
	s_waitcnt vmcnt(14)
	v_pk_fma_f32 v[146:147], v[30:31], v[130:131], v[146:147]
	v_pk_fma_f32 v[144:145], v[28:29], v[128:129], v[144:145]
	global_store_dwordx4 v[220:221], v[144:147], off offset:0
	s_waitcnt vmcnt(13)
	v_pk_fma_f32 v[150:151], v[22:23], v[134:135], v[150:151]
	v_pk_fma_f32 v[148:149], v[20:21], v[132:133], v[148:149]
	global_store_dwordx4 v[220:221], v[148:151], off offset:64
	s_waitcnt vmcnt(12)
	v_pk_fma_f32 v[154:155], v[26:27], v[138:139], v[154:155]
	v_pk_fma_f32 v[152:153], v[24:25], v[136:137], v[152:153]
	global_store_dwordx4 v[220:221], v[152:155], off offset:512
	s_waitcnt vmcnt(11)
	v_pk_fma_f32 v[158:159], v[18:19], v[142:143], v[158:159]
	v_pk_fma_f32 v[156:157], v[16:17], v[140:141], v[156:157]
	global_store_dwordx4 v[220:221], v[156:159], off offset:576
	s_waitcnt vmcnt(10)
	v_pk_fma_f32 v[162:163], v[14:15], v[130:131], v[162:163]
	v_pk_fma_f32 v[160:161], v[12:13], v[128:129], v[160:161]
	global_store_dwordx4 v[214:215], v[160:163], off offset:0
	s_waitcnt vmcnt(9)
	v_pk_fma_f32 v[236:237], v[6:7], v[134:135], v[236:237]
	v_pk_fma_f32 v[234:235], v[4:5], v[132:133], v[234:235]
	global_store_dwordx4 v[214:215], v[234:237], off offset:64
	s_waitcnt vmcnt(8)
	v_pk_fma_f32 v[240:241], v[10:11], v[138:139], v[240:241]
	v_pk_fma_f32 v[238:239], v[8:9], v[136:137], v[238:239]
	global_store_dwordx4 v[214:215], v[238:241], off offset:512
	s_waitcnt vmcnt(7)
	v_pk_fma_f32 v[244:245], v[2:3], v[142:143], v[244:245]
	v_pk_fma_f32 v[242:243], v[0:1], v[140:141], v[242:243]
	global_store_dwordx4 v[214:215], v[242:245], off offset:576
	s_branch .LBB0_341
.Ler_orig:
	global_load_dwordx4 v[132:135], v[210:211], off
	v_lshl_add_u64 v[212:213], v[128:129], 0, v[130:131]
	v_cndmask_b32_e64 v129, 0, 1, s[10:11]
	v_mov_b32_e32 v128, 0
	v_cmp_ne_u32_e64 s[8:9], 1, v129
	s_andn2_b64 vcc, exec, s[10:11]
	v_mov_b32_e32 v136, 0
	v_mov_b32_e32 v137, 0
	v_mov_b32_e32 v138, 0
	v_mov_b32_e32 v139, 0
	s_mov_b32 s12, 0x30000
	s_mov_b32 s13, 0xa0000
	s_cbranch_vccnz .LBB0_278
	global_load_dwordx4 v[136:139], v[212:213], off

; __device__ __forceinline__ void final_phase(KP P) {
;     int tid_ = threadIdx.x, bid_ = blockIdx.x; asm volatile("" : "+v"(tid_)); asm volatile("" : "+s"(bid_));
;     const int lane = tid_ & 63, gw = bid_ * 8 + (tid_ >> 6), NGW = gridDim.x * 8;
;     const float* H = (const float*)(P->ws + WS_H);
;     for (int orow = gw; orow < NB * SEQ; orow += NGW) {
;         const int b = orow / SEQ, t = orow - b * SEQ;
;         const float4* h = (const float4*)(H + (size_t)(b * RPB + t) * DM);
;         float4 v[4]; float ss = 0.f;
; #pragma unroll
;         for (int j = 0; j < 4; ++j) { v[j] = h[lane + 64 * j]; ss += v[j].x * v[j].x + v[j].y * v[j].y + v[j].z * v[j].z + v[j].w * v[j].w; }
;         const float r = rsqrtf(wave_sum(ss) * (1.f / DM) + 1e-6f);
; #pragma unroll
;         for (int j = 0; j < 4; ++j) { const int c = (lane + 64 * j) * 4; const float4 gg = *(const float4*)(P->g_final + c);
;             float4 o; o.x = v[j].x * r * gg.x; o.y = v[j].y * r * gg.y; o.z = v[j].z * r * gg.z; o.w = v[j].w * r * gg.w;
;             __builtin_nontemporal_store((f32x4){o.x, o.y, o.z, o.w}, (f32x4*)(P->out + (size_t)orow * DM + c)); }
.LBB0_446:
	s_and_b64 vcc, exec, s[2:3]
	s_cbranch_vccz .LBB0_451
	v_readfirstlane_b32 s0, v164
	s_load_dword s8, s[72:73], 0x0
	v_readlane_b32 s2, v254, 18
	v_readlane_b32 s3, v254, 19
	s_lshr_b32 s0, s0, 6
	s_lshl_b32 s6, s98, 3
	s_add_u32 s0, s0, s6
	s_load_dwordx4 s[20:23], s[2:3], 0xa8
	v_readlane_b32 s2, v254, 20
	v_readlane_b32 s3, v254, 21
	v_and_b32_e32 v88, 63, v164
	v_lshlrev_b32_e32 v80, 4, v88
	v_xor_b32_e32 v82, 1, v88
	v_lshlrev_b32_e32 v82, 2, v82
	v_xor_b32_e32 v83, 2, v88
	v_lshlrev_b32_e32 v83, 2, v83
	v_xor_b32_e32 v84, 4, v88
	v_lshlrev_b32_e32 v84, 2, v84
	v_xor_b32_e32 v85, 8, v88
	v_lshlrev_b32_e32 v85, 2, v85
	v_xor_b32_e32 v86, 16, v88
	v_lshlrev_b32_e32 v86, 2, v86
	v_xor_b32_e32 v87, 32, v88
	v_lshlrev_b32_e32 v87, 2, v87
	s_waitcnt lgkmcnt(0)
	s_lshl_b32 s8, s8, 3
	s_mov_b32 s9, 0
	global_load_dwordx4 v[64:67], v80, s[20:21] offset:0
	global_load_dwordx4 v[68:71], v80, s[20:21] offset:1024
	global_load_dwordx4 v[72:75], v80, s[20:21] offset:2048
	global_load_dwordx4 v[76:79], v80, s[20:21] offset:3072
	s_cmp_lt_u32 s0, 0x4000
	s_cbranch_scc0 .Lfn_done
	s_mov_b32 s20, s0
	s_mov_b32 s10, 0
	s_mov_b32 s11, 0
	s_mov_b32 s12, 0
	s_mov_b32 s13, 0
	s_lshr_b32 s6, s20, 13
	s_mul_i32 s6, s6, 0x100
	s_add_u32 s6, s6, s20
	s_lshl_b32 s6, s6, 12
	s_add_u32 s6, s2, s6
	s_addc_u32 s7, s3, 0
	global_load_dwordx4 v[0:3], v80, s[6:7] offset:0
	global_load_dwordx4 v[4:7], v80, s[6:7] offset:1024
	global_load_dwordx4 v[8:11], v80, s[6:7] offset:2048
	global_load_dwordx4 v[12:15], v80, s[6:7] offset:3072
	s_add_u32 s9, s9, 1
	s_mov_b32 s10, s9
	s_add_u32 s20, s20, s8
	s_cmp_lt_u32 s20, 0x4000
	s_cbranch_scc0 .Lfn_pro_done
	s_lshr_b32 s6, s20, 13
	s_mul_i32 s6, s6, 0x100
	s_add_u32 s6, s6, s20
	s_lshl_b32 s6, s6, 12
	s_add_u32 s6, s2, s6
	s_addc_u32 s7, s3, 0
	global_load_dwordx4 v[16:19], v80, s[6:7] offset:0
	global_load_dwordx4 v[20:23], v80, s[6:7] offset:1024
	global_load_dwordx4 v[24:27], v80, s[6:7] offset:2048
	global_load_dwordx4 v[28:31], v80, s[6:7] offset:3072
	s_add_u32 s9, s9, 1
	s_mov_b32 s11, s9
	s_add_u32 s20, s20, s8
	s_cmp_lt_u32 s20, 0x4000
	s_cbranch_scc0 .Lfn_pro_done
	s_lshr_b32 s6, s20, 13
	s_mul_i32 s6, s6, 0x100
	s_add_u32 s6, s6, s20
	s_lshl_b32 s6, s6, 12
	s_add_u32 s6, s2, s6
	s_addc_u32 s7, s3, 0
	global_load_dwordx4 v[32:35], v80, s[6:7] offset:0
	global_load_dwordx4 v[36:39], v80, s[6:7] offset:1024
	global_load_dwordx4 v[40:43], v80, s[6:7] offset:2048
	global_load_dwordx4 v[44:47], v80, s[6:7] offset:3072
	s_add_u32 s9, s9, 1
	s_mov_b32 s12, s9
	s_add_u32 s20, s20, s8
	s_cmp_lt_u32 s20, 0x4000
	s_cbranch_scc0 .Lfn_pro_done
	s_lshr_b32 s6, s20, 13
	s_mul_i32 s6, s6, 0x100
	s_add_u32 s6, s6, s20
	s_lshl_b32 s6, s6, 12
	s_add_u32 s6, s2, s6
	s_addc_u32 s7, s3, 0
	global_load_dwordx4 v[48:51], v80, s[6:7] offset:0
	global_load_dwordx4 v[52:55], v80, s[6:7] offset:1024
	global_load_dwordx4 v[56:59], v80, s[6:7] offset:2048
	global_load_dwordx4 v[60:63], v80, s[6:7] offset:3072
	s_add_u32 s9, s9, 1
	s_mov_b32 s13, s9
.Lfn_pro_done:
.Lfn_b0:
	s_sub_u32 s6, s9, s10
	s_cmp_ge_u32 s6, 6
	s_cbranch_scc1 .Lfn_b0_w6
	s_cmp_ge_u32 s6, 5
	s_cbranch_scc1 .Lfn_b0_w5
	s_cmp_ge_u32 s6, 4
	s_cbranch_scc1 .Lfn_b0_w4
	s_cmp_ge_u32 s6, 3
	s_cbranch_scc1 .Lfn_b0_w3
	s_cmp_ge_u32 s6, 2
	s_cbranch_scc1 .Lfn_b0_w2
	s_cmp_ge_u32 s6, 1
	s_cbranch_scc1 .Lfn_b0_w1
	s_waitcnt vmcnt(0)
	s_branch .Lfn_b0_wd
.Lfn_b0_w6:
	s_waitcnt vmcnt(24)
	s_branch .Lfn_b0_wd
.Lfn_b0_w5:
	s_waitcnt vmcnt(20)
	s_branch .Lfn_b0_wd
.Lfn_b0_w4:
	s_waitcnt vmcnt(16)
	s_branch .Lfn_b0_wd
.Lfn_b0_w3:
	s_waitcnt vmcnt(12)
	s_branch .Lfn_b0_wd
.Lfn_b0_w2:
	s_waitcnt vmcnt(8)
	s_branch .Lfn_b0_wd
.Lfn_b0_w1:
	s_waitcnt vmcnt(4)
	s_branch .Lfn_b0_wd
.Lfn_b0_wd:
	v_mul_f32_e32 v88, v1, v1
	v_fma_f32 v88, v0, v0, v88
	v_fma_f32 v88, v2, v2, v88
	v_fma_f32 v88, v3, v3, v88
	v_mul_f32_e32 v89, v5, v5
	v_fma_f32 v89, v4, v4, v89
	v_fma_f32 v89, v6, v6, v89
	v_fma_f32 v89, v7, v7, v89
	v_mul_f32_e32 v92, v9, v9
	v_fma_f32 v92, v8, v8, v92
	v_fma_f32 v92, v10, v10, v92
	v_fma_f32 v92, v11, v11, v92
	v_mul_f32_e32 v93, v13, v13
	v_fma_f32 v93, v12, v12, v93
	v_fma_f32 v93, v14, v14, v93
	v_fma_f32 v93, v15, v15, v93
	v_add_f32_e32 v88, v88, v89
	v_add_f32_e32 v88, v88, v92
	v_add_f32_e32 v88, v88, v93
	ds_bpermute_b32 v89, v82, v88
	s_waitcnt lgkmcnt(0)
	v_add_f32_e32 v88, v88, v89
	ds_bpermute_b32 v89, v83, v88
	s_waitcnt lgkmcnt(0)
	v_add_f32_e32 v88, v88, v89
	ds_bpermute_b32 v89, v84, v88
	s_waitcnt lgkmcnt(0)
	v_add_f32_e32 v88, v88, v89
	ds_bpermute_b32 v89, v85, v88
	s_waitcnt lgkmcnt(0)
	v_add_f32_e32 v88, v88, v89
	ds_bpermute_b32 v89, v86, v88
	s_waitcnt lgkmcnt(0)
	v_add_f32_e32 v88, v88, v89
	ds_bpermute_b32 v89, v87, v88
	s_waitcnt lgkmcnt(0)
	v_add_f32_e32 v88, v88, v89
	v_fmamk_f32 v88, v88, 0x3a800000, v217
	v_rsq_f32_e32 v90, v88
	s_lshl_b32 s6, s0, 12
	s_add_u32 s6, s22, s6
	s_addc_u32 s7, s23, 0
	v_pk_mul_f32 v[0:1], v[0:1], v[90:91] op_sel_hi:[1,0]
	v_pk_mul_f32 v[2:3], v[2:3], v[90:91] op_sel_hi:[1,0]
	v_pk_mul_f32 v[0:1], v[64:65], v[0:1]
	v_pk_mul_f32 v[2:3], v[66:67], v[2:3]
	v_pk_mul_f32 v[4:5], v[4:5], v[90:91] op_sel_hi:[1,0]
	v_pk_mul_f32 v[6:7], v[6:7], v[90:91] op_sel_hi:[1,0]
	v_pk_mul_f32 v[4:5], v[68:69], v[4:5]
	v_pk_mul_f32 v[6:7], v[70:71], v[6:7]
	v_pk_mul_f32 v[8:9], v[8:9], v[90:91] op_sel_hi:[1,0]
	v_pk_mul_f32 v[10:11], v[10:11], v[90:91] op_sel_hi:[1,0]
	v_pk_mul_f32 v[8:9], v[72:73], v[8:9]
	v_pk_mul_f32 v[10:11], v[74:75], v[10:11]
	v_pk_mul_f32 v[12:13], v[12:13], v[90:91] op_sel_hi:[1,0]
	v_pk_mul_f32 v[14:15], v[14:15], v[90:91] op_sel_hi:[1,0]
	v_pk_mul_f32 v[12:13], v[76:77], v[12:13]
	v_pk_mul_f32 v[14:15], v[78:79], v[14:15]
	global_store_dwordx4 v80, v[0:3], s[6:7] offset:0 nt
	global_store_dwordx4 v80, v[4:7], s[6:7] offset:1024 nt
	global_store_dwordx4 v80, v[8:11], s[6:7] offset:2048 nt
	global_store_dwordx4 v80, v[12:15], s[6:7] offset:3072 nt
	s_add_u32 s9, s9, 1
	s_mul_i32 s20, s8, 4
	s_add_u32 s20, s0, s20
	s_cmp_lt_u32 s20, 0x4000
	s_cbranch_scc0 .Lfn_b0_nopf
	s_nop 0
	s_lshr_b32 s6, s20, 13
	s_mul_i32 s6, s6, 0x100
	s_add_u32 s6, s6, s20
	s_lshl_b32 s6, s6, 12
	s_add_u32 s6, s2, s6
	s_addc_u32 s7, s3, 0
	global_load_dwordx4 v[0:3], v80, s[6:7] offset:0
	global_load_dwordx4 v[4:7], v80, s[6:7] offset:1024
	global_load_dwordx4 v[8:11], v80, s[6:7] offset:2048
	global_load_dwordx4 v[12:15], v80, s[6:7] offset:3072
	s_add_u32 s9, s9, 1
	s_mov_b32 s10, s9
.Lfn_b0_nopf:
	s_add_u32 s0, s0, s8
	s_cmp_lt_u32 s0, 0x4000
	s_cbranch_scc0 .Lfn_done
.Lfn_b1:
	s_sub_u32 s6, s9, s11
	s_cmp_ge_u32 s6, 6
	s_cbranch_scc1 .Lfn_b1_w6
	s_cmp_ge_u32 s6, 5
	s_cbranch_scc1 .Lfn_b1_w5
	s_cmp_ge_u32 s6, 4
	s_cbranch_scc1 .Lfn_b1_w4
	s_cmp_ge_u32 s6, 3
	s_cbranch_scc1 .Lfn_b1_w3
	s_cmp_ge_u32 s6, 2
	s_cbranch_scc1 .Lfn_b1_w2
	s_cmp_ge_u32 s6, 1
	s_cbranch_scc1 .Lfn_b1_w1
	s_waitcnt vmcnt(0)
	s_branch .Lfn_b1_wd

; __device__ __forceinline__ void final_phase(KP P) {
;     ...
;     for (int orow = gw; orow < NB * SEQ; orow += NGW) {
;         const int b = orow / SEQ, t = orow - b * SEQ;
;         const float4* h = (const float4*)(H + (size_t)(b * RPB + t) * DM);
;         float4 v[4]; float ss = 0.f;
; #pragma unroll
;         for (int j = 0; j < 4; ++j) { v[j] = h[lane + 64 * j]; ss += v[j].x * v[j].x + v[j].y * v[j].y + v[j].z * v[j].z + v[j].w * v[j].w; }
;         const float r = rsqrtf(wave_sum(ss) * (1.f / DM) + 1e-6f);
; #pragma unroll
;         for (int j = 0; j < 4; ++j) { const int c = (lane + 64 * j) * 4; const float4 gg = *(const float4*)(P->g_final + c);
;             float4 o; o.x = v[j].x * r * gg.x; o.y = v[j].y * r * gg.y; o.z = v[j].z * r * gg.z; o.w = v[j].w * r * gg.w;
;             __builtin_nontemporal_store((f32x4){o.x, o.y, o.z, o.w}, (f32x4*)(P->out + (size_t)orow * DM + c)); }
.Lfn_b1_w2:
	s_waitcnt vmcnt(8)
	s_branch .Lfn_b1_wd
.Lfn_b1_w1:
	s_waitcnt vmcnt(4)
	s_branch .Lfn_b1_wd
.Lfn_b1_wd:
	v_mul_f32_e32 v88, v17, v17
	v_fma_f32 v88, v16, v16, v88
	v_fma_f32 v88, v18, v18, v88
	v_fma_f32 v88, v19, v19, v88
	v_mul_f32_e32 v89, v21, v21
	v_fma_f32 v89, v20, v20, v89
	v_fma_f32 v89, v22, v22, v89
	v_fma_f32 v89, v23, v23, v89
	v_mul_f32_e32 v92, v25, v25
	v_fma_f32 v92, v24, v24, v92
	v_fma_f32 v92, v26, v26, v92
	v_fma_f32 v92, v27, v27, v92
	v_mul_f32_e32 v93, v29, v29
	v_fma_f32 v93, v28, v28, v93
	v_fma_f32 v93, v30, v30, v93
	v_fma_f32 v93, v31, v31, v93
	v_add_f32_e32 v88, v88, v89
	v_add_f32_e32 v88, v88, v92
	v_add_f32_e32 v88, v88, v93
	ds_bpermute_b32 v89, v82, v88
	s_waitcnt lgkmcnt(0)
	v_add_f32_e32 v88, v88, v89
	ds_bpermute_b32 v89, v83, v88
	s_waitcnt lgkmcnt(0)
	v_add_f32_e32 v88, v88, v89
	ds_bpermute_b32 v89, v84, v88
	s_waitcnt lgkmcnt(0)
	v_add_f32_e32 v88, v88, v89
	ds_bpermute_b32 v89, v85, v88
	s_waitcnt lgkmcnt(0)
	v_add_f32_e32 v88, v88, v89
	ds_bpermute_b32 v89, v86, v88
	s_waitcnt lgkmcnt(0)
	v_add_f32_e32 v88, v88, v89
	ds_bpermute_b32 v89, v87, v88
	s_waitcnt lgkmcnt(0)
	v_add_f32_e32 v88, v88, v89
	v_fmamk_f32 v88, v88, 0x3a800000, v217
	v_rsq_f32_e32 v90, v88
	s_lshl_b32 s6, s0, 12
	s_add_u32 s6, s22, s6
	s_addc_u32 s7, s23, 0
	v_pk_mul_f32 v[16:17], v[16:17], v[90:91] op_sel_hi:[1,0]
	v_pk_mul_f32 v[18:19], v[18:19], v[90:91] op_sel_hi:[1,0]
	v_pk_mul_f32 v[16:17], v[64:65], v[16:17]
	v_pk_mul_f32 v[18:19], v[66:67], v[18:19]
	v_pk_mul_f32 v[20:21], v[20:21], v[90:91] op_sel_hi:[1,0]
	v_pk_mul_f32 v[22:23], v[22:23], v[90:91] op_sel_hi:[1,0]
	v_pk_mul_f32 v[20:21], v[68:69], v[20:21]
	v_pk_mul_f32 v[22:23], v[70:71], v[22:23]
	v_pk_mul_f32 v[24:25], v[24:25], v[90:91] op_sel_hi:[1,0]
	v_pk_mul_f32 v[26:27], v[26:27], v[90:91] op_sel_hi:[1,0]
	v_pk_mul_f32 v[24:25], v[72:73], v[24:25]
	v_pk_mul_f32 v[26:27], v[74:75], v[26:27]
	v_pk_mul_f32 v[28:29], v[28:29], v[90:91] op_sel_hi:[1,0]
	v_pk_mul_f32 v[30:31], v[30:31], v[90:91] op_sel_hi:[1,0]
	v_pk_mul_f32 v[28:29], v[76:77], v[28:29]
	v_pk_mul_f32 v[30:31], v[78:79], v[30:31]
	global_store_dwordx4 v80, v[16:19], s[6:7] offset:0 nt
	global_store_dwordx4 v80, v[20:23], s[6:7] offset:1024 nt
	global_store_dwordx4 v80, v[24:27], s[6:7] offset:2048 nt
	global_store_dwordx4 v80, v[28:31], s[6:7] offset:3072 nt
	s_add_u32 s9, s9, 1
	s_mul_i32 s20, s8, 4
	s_add_u32 s20, s0, s20
	s_cmp_lt_u32 s20, 0x4000
	s_cbranch_scc0 .Lfn_b1_nopf
	s_nop 0
	s_lshr_b32 s6, s20, 13
	s_mul_i32 s6, s6, 0x100
	s_add_u32 s6, s6, s20
	s_lshl_b32 s6, s6, 12
	s_add_u32 s6, s2, s6
	s_addc_u32 s7, s3, 0
	global_load_dwordx4 v[16:19], v80, s[6:7] offset:0
	global_load_dwordx4 v[20:23], v80, s[6:7] offset:1024
	global_load_dwordx4 v[24:27], v80, s[6:7] offset:2048
	global_load_dwordx4 v[28:31], v80, s[6:7] offset:3072
	s_add_u32 s9, s9, 1
	s_mov_b32 s11, s9

; __device__ __forceinline__ void final_phase(KP P) {
;     ...
;     for (int orow = gw; orow < NB * SEQ; orow += NGW) {
;         const int b = orow / SEQ, t = orow - b * SEQ;
;         const float4* h = (const float4*)(H + (size_t)(b * RPB + t) * DM);
;         float4 v[4]; float ss = 0.f;
; #pragma unroll
;         for (int j = 0; j < 4; ++j) { v[j] = h[lane + 64 * j]; ss += v[j].x * v[j].x + v[j].y * v[j].y + v[j].z * v[j].z + v[j].w * v[j].w; }
.Lfn_b2:
	s_sub_u32 s6, s9, s12
	s_cmp_ge_u32 s6, 6
	s_cbranch_scc1 .Lfn_b2_w6
	s_cmp_ge_u32 s6, 5
	s_cbranch_scc1 .Lfn_b2_w5
	s_cmp_ge_u32 s6, 4
	s_cbranch_scc1 .Lfn_b2_w4
	s_cmp_ge_u32 s6, 3
	s_cbranch_scc1 .Lfn_b2_w3
	s_cmp_ge_u32 s6, 2
	s_cbranch_scc1 .Lfn_b2_w2
	s_cmp_ge_u32 s6, 1
	s_cbranch_scc1 .Lfn_b2_w1
	s_waitcnt vmcnt(0)
	s_branch .Lfn_b2_wd

; __device__ __forceinline__ void final_phase(KP P) {
;     ...
;     for (int orow = gw; orow < NB * SEQ; orow += NGW) {
;         const int b = orow / SEQ, t = orow - b * SEQ;
;         const float4* h = (const float4*)(H + (size_t)(b * RPB + t) * DM);
;         float4 v[4]; float ss = 0.f;
; #pragma unroll
;         for (int j = 0; j < 4; ++j) { v[j] = h[lane + 64 * j]; ss += v[j].x * v[j].x + v[j].y * v[j].y + v[j].z * v[j].z + v[j].w * v[j].w; }
;         const float r = rsqrtf(wave_sum(ss) * (1.f / DM) + 1e-6f);
; #pragma unroll
;         for (int j = 0; j < 4; ++j) { const int c = (lane + 64 * j) * 4; const float4 gg = *(const float4*)(P->g_final + c);
;             float4 o; o.x = v[j].x * r * gg.x; o.y = v[j].y * r * gg.y; o.z = v[j].z * r * gg.z; o.w = v[j].w * r * gg.w;
;             __builtin_nontemporal_store((f32x4){o.x, o.y, o.z, o.w}, (f32x4*)(P->out + (size_t)orow * DM + c)); }
.Lfn_b2_w2:
	s_waitcnt vmcnt(8)
	s_branch .Lfn_b2_wd
.Lfn_b2_w1:
	s_waitcnt vmcnt(4)
	s_branch .Lfn_b2_wd
.Lfn_b2_wd:
	v_mul_f32_e32 v88, v33, v33
	v_fma_f32 v88, v32, v32, v88
	v_fma_f32 v88, v34, v34, v88
	v_fma_f32 v88, v35, v35, v88
	v_mul_f32_e32 v89, v37, v37
	v_fma_f32 v89, v36, v36, v89
	v_fma_f32 v89, v38, v38, v89
	v_fma_f32 v89, v39, v39, v89
	v_mul_f32_e32 v92, v41, v41
	v_fma_f32 v92, v40, v40, v92
	v_fma_f32 v92, v42, v42, v92
	v_fma_f32 v92, v43, v43, v92
	v_mul_f32_e32 v93, v45, v45
	v_fma_f32 v93, v44, v44, v93
	v_fma_f32 v93, v46, v46, v93
	v_fma_f32 v93, v47, v47, v93
	v_add_f32_e32 v88, v88, v89
	v_add_f32_e32 v88, v88, v92
	v_add_f32_e32 v88, v88, v93
	ds_bpermute_b32 v89, v82, v88
	s_waitcnt lgkmcnt(0)
	v_add_f32_e32 v88, v88, v89
	ds_bpermute_b32 v89, v83, v88
	s_waitcnt lgkmcnt(0)
	v_add_f32_e32 v88, v88, v89
	ds_bpermute_b32 v89, v84, v88
	s_waitcnt lgkmcnt(0)
	v_add_f32_e32 v88, v88, v89
	ds_bpermute_b32 v89, v85, v88
	s_waitcnt lgkmcnt(0)
	v_add_f32_e32 v88, v88, v89
	ds_bpermute_b32 v89, v86, v88
	s_waitcnt lgkmcnt(0)
	v_add_f32_e32 v88, v88, v89
	ds_bpermute_b32 v89, v87, v88
	s_waitcnt lgkmcnt(0)
	v_add_f32_e32 v88, v88, v89
	v_fmamk_f32 v88, v88, 0x3a800000, v217
	v_rsq_f32_e32 v90, v88
	s_lshl_b32 s6, s0, 12
	s_add_u32 s6, s22, s6
	s_addc_u32 s7, s23, 0
	v_pk_mul_f32 v[32:33], v[32:33], v[90:91] op_sel_hi:[1,0]
	v_pk_mul_f32 v[34:35], v[34:35], v[90:91] op_sel_hi:[1,0]
	v_pk_mul_f32 v[32:33], v[64:65], v[32:33]
	v_pk_mul_f32 v[34:35], v[66:67], v[34:35]
	v_pk_mul_f32 v[36:37], v[36:37], v[90:91] op_sel_hi:[1,0]
	v_pk_mul_f32 v[38:39], v[38:39], v[90:91] op_sel_hi:[1,0]
	v_pk_mul_f32 v[36:37], v[68:69], v[36:37]
	v_pk_mul_f32 v[38:39], v[70:71], v[38:39]
	v_pk_mul_f32 v[40:41], v[40:41], v[90:91] op_sel_hi:[1,0]
	v_pk_mul_f32 v[42:43], v[42:43], v[90:91] op_sel_hi:[1,0]
	v_pk_mul_f32 v[40:41], v[72:73], v[40:41]
	v_pk_mul_f32 v[42:43], v[74:75], v[42:43]
	v_pk_mul_f32 v[44:45], v[44:45], v[90:91] op_sel_hi:[1,0]
	v_pk_mul_f32 v[46:47], v[46:47], v[90:91] op_sel_hi:[1,0]
	v_pk_mul_f32 v[44:45], v[76:77], v[44:45]
	v_pk_mul_f32 v[46:47], v[78:79], v[46:47]
	global_store_dwordx4 v80, v[32:35], s[6:7] offset:0 nt
	global_store_dwordx4 v80, v[36:39], s[6:7] offset:1024 nt
	global_store_dwordx4 v80, v[40:43], s[6:7] offset:2048 nt
	global_store_dwordx4 v80, v[44:47], s[6:7] offset:3072 nt
	s_add_u32 s9, s9, 1
	s_mul_i32 s20, s8, 4
	s_add_u32 s20, s0, s20
	s_cmp_lt_u32 s20, 0x4000
	s_cbranch_scc0 .Lfn_b2_nopf
	s_nop 0
	s_lshr_b32 s6, s20, 13
	s_mul_i32 s6, s6, 0x100
	s_add_u32 s6, s6, s20
	s_lshl_b32 s6, s6, 12
	s_add_u32 s6, s2, s6
	s_addc_u32 s7, s3, 0
	global_load_dwordx4 v[32:35], v80, s[6:7] offset:0
	global_load_dwordx4 v[36:39], v80, s[6:7] offset:1024
	global_load_dwordx4 v[40:43], v80, s[6:7] offset:2048
	global_load_dwordx4 v[44:47], v80, s[6:7] offset:3072
	s_add_u32 s9, s9, 1
	s_mov_b32 s12, s9

; __device__ __forceinline__ void final_phase(KP P) {
;     ...
;     for (int orow = gw; orow < NB * SEQ; orow += NGW) {
;         const int b = orow / SEQ, t = orow - b * SEQ;
;         const float4* h = (const float4*)(H + (size_t)(b * RPB + t) * DM);
;         float4 v[4]; float ss = 0.f;
; #pragma unroll
;         for (int j = 0; j < 4; ++j) { v[j] = h[lane + 64 * j]; ss += v[j].x * v[j].x + v[j].y * v[j].y + v[j].z * v[j].z + v[j].w * v[j].w; }
.Lfn_b3:
	s_sub_u32 s6, s9, s13
	s_cmp_ge_u32 s6, 6
	s_cbranch_scc1 .Lfn_b3_w6
	s_cmp_ge_u32 s6, 5
	s_cbranch_scc1 .Lfn_b3_w5
	s_cmp_ge_u32 s6, 4
	s_cbranch_scc1 .Lfn_b3_w4
	s_cmp_ge_u32 s6, 3
	s_cbranch_scc1 .Lfn_b3_w3
	s_cmp_ge_u32 s6, 2
	s_cbranch_scc1 .Lfn_b3_w2
	s_cmp_ge_u32 s6, 1
	s_cbranch_scc1 .Lfn_b3_w1
	s_waitcnt vmcnt(0)
	s_branch .Lfn_b3_wd

; __device__ __forceinline__ void final_phase(KP P) {
;     ...
;     for (int orow = gw; orow < NB * SEQ; orow += NGW) {
;         const int b = orow / SEQ, t = orow - b * SEQ;
;         const float4* h = (const float4*)(H + (size_t)(b * RPB + t) * DM);
;         float4 v[4]; float ss = 0.f;
; #pragma unroll
;         for (int j = 0; j < 4; ++j) { v[j] = h[lane + 64 * j]; ss += v[j].x * v[j].x + v[j].y * v[j].y + v[j].z * v[j].z + v[j].w * v[j].w; }
;         const float r = rsqrtf(wave_sum(ss) * (1.f / DM) + 1e-6f);
; #pragma unroll
;         for (int j = 0; j < 4; ++j) { const int c = (lane + 64 * j) * 4; const float4 gg = *(const float4*)(P->g_final + c);
;             float4 o; o.x = v[j].x * r * gg.x; o.y = v[j].y * r * gg.y; o.z = v[j].z * r * gg.z; o.w = v[j].w * r * gg.w;
;             __builtin_nontemporal_store((f32x4){o.x, o.y, o.z, o.w}, (f32x4*)(P->out + (size_t)orow * DM + c)); }
.Lfn_b3_w2:
	s_waitcnt vmcnt(8)
	s_branch .Lfn_b3_wd
.Lfn_b3_w1:
	s_waitcnt vmcnt(4)
	s_branch .Lfn_b3_wd
.Lfn_b3_wd:
	v_mul_f32_e32 v88, v49, v49
	v_fma_f32 v88, v48, v48, v88
	v_fma_f32 v88, v50, v50, v88
	v_fma_f32 v88, v51, v51, v88
	v_mul_f32_e32 v89, v53, v53
	v_fma_f32 v89, v52, v52, v89
	v_fma_f32 v89, v54, v54, v89
	v_fma_f32 v89, v55, v55, v89
	v_mul_f32_e32 v92, v57, v57
	v_fma_f32 v92, v56, v56, v92
	v_fma_f32 v92, v58, v58, v92
	v_fma_f32 v92, v59, v59, v92
	v_mul_f32_e32 v93, v61, v61
	v_fma_f32 v93, v60, v60, v93
	v_fma_f32 v93, v62, v62, v93
	v_fma_f32 v93, v63, v63, v93
	v_add_f32_e32 v88, v88, v89
	v_add_f32_e32 v88, v88, v92
	v_add_f32_e32 v88, v88, v93
	ds_bpermute_b32 v89, v82, v88
	s_waitcnt lgkmcnt(0)
	v_add_f32_e32 v88, v88, v89
	ds_bpermute_b32 v89, v83, v88
	s_waitcnt lgkmcnt(0)
	v_add_f32_e32 v88, v88, v89
	ds_bpermute_b32 v89, v84, v88
	s_waitcnt lgkmcnt(0)
	v_add_f32_e32 v88, v88, v89
	ds_bpermute_b32 v89, v85, v88
	s_waitcnt lgkmcnt(0)
	v_add_f32_e32 v88, v88, v89
	ds_bpermute_b32 v89, v86, v88
	s_waitcnt lgkmcnt(0)
	v_add_f32_e32 v88, v88, v89
	ds_bpermute_b32 v89, v87, v88
	s_waitcnt lgkmcnt(0)
	v_add_f32_e32 v88, v88, v89
	v_fmamk_f32 v88, v88, 0x3a800000, v217
	v_rsq_f32_e32 v90, v88
	s_lshl_b32 s6, s0, 12
	s_add_u32 s6, s22, s6
	s_addc_u32 s7, s23, 0
	v_pk_mul_f32 v[48:49], v[48:49], v[90:91] op_sel_hi:[1,0]
	v_pk_mul_f32 v[50:51], v[50:51], v[90:91] op_sel_hi:[1,0]
	v_pk_mul_f32 v[48:49], v[64:65], v[48:49]
	v_pk_mul_f32 v[50:51], v[66:67], v[50:51]
	v_pk_mul_f32 v[52:53], v[52:53], v[90:91] op_sel_hi:[1,0]
	v_pk_mul_f32 v[54:55], v[54:55], v[90:91] op_sel_hi:[1,0]
	v_pk_mul_f32 v[52:53], v[68:69], v[52:53]
	v_pk_mul_f32 v[54:55], v[70:71], v[54:55]
	v_pk_mul_f32 v[56:57], v[56:57], v[90:91] op_sel_hi:[1,0]
	v_pk_mul_f32 v[58:59], v[58:59], v[90:91] op_sel_hi:[1,0]
	v_pk_mul_f32 v[56:57], v[72:73], v[56:57]
	v_pk_mul_f32 v[58:59], v[74:75], v[58:59]
	v_pk_mul_f32 v[60:61], v[60:61], v[90:91] op_sel_hi:[1,0]
	v_pk_mul_f32 v[62:63], v[62:63], v[90:91] op_sel_hi:[1,0]
	v_pk_mul_f32 v[60:61], v[76:77], v[60:61]
	v_pk_mul_f32 v[62:63], v[78:79], v[62:63]
	global_store_dwordx4 v80, v[48:51], s[6:7] offset:0 nt
	global_store_dwordx4 v80, v[52:55], s[6:7] offset:1024 nt
	global_store_dwordx4 v80, v[56:59], s[6:7] offset:2048 nt
	global_store_dwordx4 v80, v[60:63], s[6:7] offset:3072 nt
	s_add_u32 s9, s9, 1
	s_mul_i32 s20, s8, 4
	s_add_u32 s20, s0, s20
	s_cmp_lt_u32 s20, 0x4000
	s_cbranch_scc0 .Lfn_b3_nopf
	s_nop 0
	s_lshr_b32 s6, s20, 13
	s_mul_i32 s6, s6, 0x100
	s_add_u32 s6, s6, s20
	s_lshl_b32 s6, s6, 12
	s_add_u32 s6, s2, s6
	s_addc_u32 s7, s3, 0
	global_load_dwordx4 v[48:51], v80, s[6:7] offset:0
	global_load_dwordx4 v[52:55], v80, s[6:7] offset:1024
	global_load_dwordx4 v[56:59], v80, s[6:7] offset:2048
	global_load_dwordx4 v[60:63], v80, s[6:7] offset:3072
	s_add_u32 s9, s9, 1
	s_mov_b32 s13, s9
.Lfn_b3_nopf:
	s_add_u32 s0, s0, s8
	s_cmp_lt_u32 s0, 0x4000
	s_cbranch_scc0 .Lfn_done
	s_branch .Lfn_b0
.Lfn_done:
	s_mov_b64 s[6:7], 0
.LBB0_450:
	s_or_b64 exec, exec, s[6:7]
	s_mov_b64 s[12:13], -1

; __device__ __forceinline__ void prologue_phase(KP P, LAS unsigned char* lds) {
;     ...
;             const int ks = wave * 128 + 16 * (lane >> 3);
; #pragma unroll
;             for (int j = 0; j < 16; ++j) { const float w = __builtin_nontemporal_load(W + (size_t)(ks + j) * NMOD + 64 + (lane & 7)); e0 += sv[ks + j] * w; e1 += sv[1024 + ks + j] * w; e2 += sv[2048 + ks + j] * w; }
; #pragma unroll 32
;             for (int k = wave * 128; k < wave * 128 + 128; ++k) { const float w = __builtin_nontemporal_load(W + (size_t)k * NMOD + lane); a0 += sv[k] * w; a1 += sv[1024 + k] * w; a2 += sv[2048 + k] * w; }
; #pragma unroll
;             for (int o = 8; o < 64; o <<= 1) { e0 += __shfl_xor(e0, o); e1 += __shfl_xor(e1, o); e2 += __shfl_xor(e2, o); }
;             red[(wave * 3 + 0) * 72 + lane] = a0; red[(wave * 3 + 1) * 72 + lane] = a1; red[(wave * 3 + 2) * 72 + lane] = a2;
;             if (lane < 8) { red[(wave * 3 + 0) * 72 + 64 + lane] = e0; red[(wave * 3 + 1) * 72 + 64 + lane] = e1; red[(wave * 3 + 2) * 72 + 64 + lane] = e2; }
.LBB0_489:
	v_lshl_add_u64 v[94:95], v[92:93], 0, s[22:23]
	s_mov_b32 s9, 0
	global_load_dword v200, v[94:95], off nt
	s_mov_b32 s8, 0x9000
	v_lshl_add_u64 v[48:49], v[94:95], 0, s[8:9]
	global_load_dword v201, v[48:49], off nt
	s_mov_b32 s8, 0x12000
	v_lshl_add_u64 v[48:49], v[94:95], 0, s[8:9]
	global_load_dword v202, v[48:49], off nt
	s_mov_b32 s8, 0x1b000
	v_lshl_add_u64 v[48:49], v[94:95], 0, s[8:9]
	global_load_dword v203, v[48:49], off nt
	s_mov_b32 s8, 0x24000
	v_lshl_add_u64 v[48:49], v[94:95], 0, s[8:9]
	global_load_dword v204, v[48:49], off nt
	s_mov_b32 s8, 0x2d000
	v_lshl_add_u64 v[48:49], v[94:95], 0, s[8:9]
	global_load_dword v205, v[48:49], off nt
	s_mov_b32 s8, 0x36000
	v_lshl_add_u64 v[48:49], v[94:95], 0, s[8:9]
	global_load_dword v206, v[48:49], off nt
	s_mov_b32 s8, 0x3f000
	v_lshl_add_u64 v[48:49], v[94:95], 0, s[8:9]
	global_load_dword v207, v[48:49], off nt
	s_mov_b32 s8, 0x48000
	v_lshl_add_u64 v[48:49], v[94:95], 0, s[8:9]
	global_load_dword v208, v[48:49], off nt
	s_mov_b32 s8, 0x51000
	v_lshl_add_u64 v[48:49], v[94:95], 0, s[8:9]
	global_load_dword v209, v[48:49], off nt
	s_mov_b32 s8, 0x5a000
	v_lshl_add_u64 v[48:49], v[94:95], 0, s[8:9]
	global_load_dword v210, v[48:49], off nt
	s_mov_b32 s8, 0x63000
	v_lshl_add_u64 v[48:49], v[94:95], 0, s[8:9]
	global_load_dword v211, v[48:49], off nt
	s_mov_b32 s8, 0x6c000
	v_lshl_add_u64 v[48:49], v[94:95], 0, s[8:9]
	global_load_dword v212, v[48:49], off nt
	s_mov_b32 s8, 0x75000
	v_lshl_add_u64 v[48:49], v[94:95], 0, s[8:9]
	global_load_dword v213, v[48:49], off nt
	s_mov_b32 s8, 0x7e000
	v_lshl_add_u64 v[48:49], v[94:95], 0, s[8:9]
	global_load_dword v214, v[48:49], off nt
	s_mov_b32 s8, 0x87000
	v_lshl_add_u64 v[48:49], v[94:95], 0, s[8:9]
	global_load_dword v215, v[48:49], off nt
	s_mov_b32 s8, 0x90000
	v_lshl_add_u64 v[48:49], v[94:95], 0, s[8:9]
	global_load_dword v230, v[48:49], off nt
	s_mov_b32 s8, 0x99000
	v_lshl_add_u64 v[48:49], v[94:95], 0, s[8:9]
	global_load_dword v231, v[48:49], off nt
	s_mov_b32 s8, 0xa2000
	v_lshl_add_u64 v[48:49], v[94:95], 0, s[8:9]
	global_load_dword v232, v[48:49], off nt
	s_mov_b32 s8, 0xab000
	v_lshl_add_u64 v[48:49], v[94:95], 0, s[8:9]
	global_load_dword v233, v[48:49], off nt
	s_mov_b32 s8, 0xb4000
	v_lshl_add_u64 v[48:49], v[94:95], 0, s[8:9]
	global_load_dword v234, v[48:49], off nt
	s_mov_b32 s8, 0xbd000
	v_lshl_add_u64 v[48:49], v[94:95], 0, s[8:9]
	global_load_dword v235, v[48:49], off nt
	s_mov_b32 s8, 0xc6000
	v_lshl_add_u64 v[48:49], v[94:95], 0, s[8:9]
	global_load_dword v236, v[48:49], off nt
	s_mov_b32 s8, 0xcf000
	v_lshl_add_u64 v[48:49], v[94:95], 0, s[8:9]
	global_load_dword v237, v[48:49], off nt
	s_mov_b32 s8, 0xd8000
	v_lshl_add_u64 v[48:49], v[94:95], 0, s[8:9]
	global_load_dword v238, v[48:49], off nt
	s_mov_b32 s8, 0xe1000
	v_lshl_add_u64 v[48:49], v[94:95], 0, s[8:9]
	global_load_dword v239, v[48:49], off nt
	s_mov_b32 s8, 0xea000
	v_lshl_add_u64 v[48:49], v[94:95], 0, s[8:9]
	global_load_dword v240, v[48:49], off nt
	s_mov_b32 s8, 0xf3000
	v_lshl_add_u64 v[48:49], v[94:95], 0, s[8:9]
	global_load_dword v241, v[48:49], off nt
	s_mov_b32 s8, 0xfc000
	v_lshl_add_u64 v[48:49], v[94:95], 0, s[8:9]
	global_load_dword v242, v[48:49], off nt
	s_mov_b32 s8, 0x105000
	v_lshl_add_u64 v[48:49], v[94:95], 0, s[8:9]
	global_load_dword v243, v[48:49], off nt
	s_mov_b32 s8, 0x10e000
	v_lshl_add_u64 v[48:49], v[94:95], 0, s[8:9]
	global_load_dword v244, v[48:49], off nt
	s_mov_b32 s8, 0x117000
	v_lshl_add_u64 v[48:49], v[94:95], 0, s[8:9]
	global_load_dword v245, v[48:49], off nt
	s_add_u32 s22, s22, 0x120000
	s_addc_u32 s23, s23, 0
	ds_read_b128 v[122:125], v121 offset:0
	ds_read_b128 v[126:129], v121 offset:16
	ds_read_b128 v[130:133], v121 offset:4096
	ds_read_b128 v[134:137], v121 offset:4112
	ds_read_b128 v[138:141], v121 offset:8192
	ds_read_b128 v[226:229], v121 offset:8208
	s_waitcnt lgkmcnt(0)
	s_waitcnt vmcnt(31)
	v_fmac_f32_e32 v96, v200, v122
	v_fmac_f32_e32 v97, v200, v130
	v_fmac_f32_e32 v104, v200, v138
	s_waitcnt vmcnt(30)
	v_fmac_f32_e32 v96, v201, v123
	v_fmac_f32_e32 v97, v201, v131
	v_fmac_f32_e32 v104, v201, v139
	s_waitcnt vmcnt(29)
	v_fmac_f32_e32 v96, v202, v124
	v_fmac_f32_e32 v97, v202, v132
	v_fmac_f32_e32 v104, v202, v140
	s_waitcnt vmcnt(28)
	v_fmac_f32_e32 v96, v203, v125
	v_fmac_f32_e32 v97, v203, v133
	v_fmac_f32_e32 v104, v203, v141
	s_waitcnt vmcnt(27)
	v_fmac_f32_e32 v96, v204, v126
	v_fmac_f32_e32 v97, v204, v134
	v_fmac_f32_e32 v104, v204, v226
	s_waitcnt vmcnt(26)
	v_fmac_f32_e32 v96, v205, v127
	v_fmac_f32_e32 v97, v205, v135
	v_fmac_f32_e32 v104, v205, v227
	s_waitcnt vmcnt(25)
	v_fmac_f32_e32 v96, v206, v128
	v_fmac_f32_e32 v97, v206, v136
	v_fmac_f32_e32 v104, v206, v228
	s_waitcnt vmcnt(24)
	v_fmac_f32_e32 v96, v207, v129
	v_fmac_f32_e32 v97, v207, v137
	v_fmac_f32_e32 v104, v207, v229
	ds_read_b128 v[122:125], v121 offset:32
	ds_read_b128 v[126:129], v121 offset:48
	ds_read_b128 v[130:133], v121 offset:4128
	ds_read_b128 v[134:137], v121 offset:4144
	ds_read_b128 v[138:141], v121 offset:8224
	ds_read_b128 v[226:229], v121 offset:8240
	s_waitcnt lgkmcnt(0)
	s_waitcnt vmcnt(23)
	v_fmac_f32_e32 v96, v208, v122
	v_fmac_f32_e32 v97, v208, v130
	v_fmac_f32_e32 v104, v208, v138
	s_waitcnt vmcnt(22)
	v_fmac_f32_e32 v96, v209, v123
	v_fmac_f32_e32 v97, v209, v131
	v_fmac_f32_e32 v104, v209, v139
	s_waitcnt vmcnt(21)
	v_fmac_f32_e32 v96, v210, v124
	v_fmac_f32_e32 v97, v210, v132
	v_fmac_f32_e32 v104, v210, v140
	s_waitcnt vmcnt(20)
; __device__ __forceinline__ void prologue_phase(KP P, LAS unsigned char* lds) {
;     ...
; #pragma unroll
;             for (int j = 0; j < 16; ++j) { const float w = __builtin_nontemporal_load(W + (size_t)(ks + j) * NMOD + 64 + (lane & 7)); e0 += sv[ks + j] * w; e1 += sv[1024 + ks + j] * w; e2 += sv[2048 + ks + j] * w; }
; #pragma unroll 32
;             for (int k = wave * 128; k < wave * 128 + 128; ++k) { const float w = __builtin_nontemporal_load(W + (size_t)k * NMOD + lane); a0 += sv[k] * w; a1 += sv[1024 + k] * w; a2 += sv[2048 + k] * w; }
; #pragma unroll
;             for (int o = 8; o < 64; o <<= 1) { e0 += __shfl_xor(e0, o); e1 += __shfl_xor(e1, o); e2 += __shfl_xor(e2, o); }
;             red[(wave * 3 + 0) * 72 + lane] = a0; red[(wave * 3 + 1) * 72 + lane] = a1; red[(wave * 3 + 2) * 72 + lane] = a2;
;             if (lane < 8) { red[(wave * 3 + 0) * 72 + 64 + lane] = e0; red[(wave * 3 + 1) * 72 + 64 + lane] = e1; red[(wave * 3 + 2) * 72 + 64 + lane] = e2; }
	v_fmac_f32_e32 v96, v211, v125
	v_fmac_f32_e32 v97, v211, v133
	v_fmac_f32_e32 v104, v211, v141
	s_waitcnt vmcnt(19)
	v_fmac_f32_e32 v96, v212, v126
	v_fmac_f32_e32 v97, v212, v134
	v_fmac_f32_e32 v104, v212, v226
	s_waitcnt vmcnt(18)
	v_fmac_f32_e32 v96, v213, v127
	v_fmac_f32_e32 v97, v213, v135
	v_fmac_f32_e32 v104, v213, v227
	s_waitcnt vmcnt(17)
	v_fmac_f32_e32 v96, v214, v128
	v_fmac_f32_e32 v97, v214, v136
	v_fmac_f32_e32 v104, v214, v228
	s_waitcnt vmcnt(16)
	v_fmac_f32_e32 v96, v215, v129
	v_fmac_f32_e32 v97, v215, v137
	v_fmac_f32_e32 v104, v215, v229
	ds_read_b128 v[122:125], v121 offset:64
	ds_read_b128 v[126:129], v121 offset:80
	ds_read_b128 v[130:133], v121 offset:4160
	ds_read_b128 v[134:137], v121 offset:4176
	ds_read_b128 v[138:141], v121 offset:8256
	ds_read_b128 v[226:229], v121 offset:8272
	s_waitcnt lgkmcnt(0)
	s_waitcnt vmcnt(15)
	v_fmac_f32_e32 v96, v230, v122
	v_fmac_f32_e32 v97, v230, v130
	v_fmac_f32_e32 v104, v230, v138
	s_waitcnt vmcnt(14)
	v_fmac_f32_e32 v96, v231, v123
	v_fmac_f32_e32 v97, v231, v131
	v_fmac_f32_e32 v104, v231, v139
	s_waitcnt vmcnt(13)
	v_fmac_f32_e32 v96, v232, v124
	v_fmac_f32_e32 v97, v232, v132
	v_fmac_f32_e32 v104, v232, v140
	s_waitcnt vmcnt(12)
	v_fmac_f32_e32 v96, v233, v125
	v_fmac_f32_e32 v97, v233, v133
	v_fmac_f32_e32 v104, v233, v141
	s_waitcnt vmcnt(11)
	v_fmac_f32_e32 v96, v234, v126
	v_fmac_f32_e32 v97, v234, v134
	v_fmac_f32_e32 v104, v234, v226
	s_waitcnt vmcnt(10)
	v_fmac_f32_e32 v96, v235, v127
	v_fmac_f32_e32 v97, v235, v135
	v_fmac_f32_e32 v104, v235, v227
	s_waitcnt vmcnt(9)
	v_fmac_f32_e32 v96, v236, v128
	v_fmac_f32_e32 v97, v236, v136
	v_fmac_f32_e32 v104, v236, v228
	s_waitcnt vmcnt(8)
	v_fmac_f32_e32 v96, v237, v129
	v_fmac_f32_e32 v97, v237, v137
	v_fmac_f32_e32 v104, v237, v229
	ds_read_b128 v[122:125], v121 offset:96
	ds_read_b128 v[126:129], v121 offset:112
	ds_read_b128 v[130:133], v121 offset:4192
	ds_read_b128 v[134:137], v121 offset:4208
	ds_read_b128 v[138:141], v121 offset:8288
	ds_read_b128 v[226:229], v121 offset:8304
	s_waitcnt lgkmcnt(0)
	s_waitcnt vmcnt(7)
	v_fmac_f32_e32 v96, v238, v122
	v_fmac_f32_e32 v97, v238, v130
	v_fmac_f32_e32 v104, v238, v138
	s_waitcnt vmcnt(6)
	v_fmac_f32_e32 v96, v239, v123
	v_fmac_f32_e32 v97, v239, v131
	v_fmac_f32_e32 v104, v239, v139
	s_waitcnt vmcnt(5)
	v_fmac_f32_e32 v96, v240, v124
	v_fmac_f32_e32 v97, v240, v132
	v_fmac_f32_e32 v104, v240, v140
	s_waitcnt vmcnt(4)
	v_fmac_f32_e32 v96, v241, v125
	v_fmac_f32_e32 v97, v241, v133
	v_fmac_f32_e32 v104, v241, v141
	s_waitcnt vmcnt(3)
	v_fmac_f32_e32 v96, v242, v126
	v_fmac_f32_e32 v97, v242, v134
	v_fmac_f32_e32 v104, v242, v226
	s_waitcnt vmcnt(2)
	v_fmac_f32_e32 v96, v243, v127
	v_fmac_f32_e32 v97, v243, v135
	v_fmac_f32_e32 v104, v243, v227
	s_waitcnt vmcnt(1)
	v_fmac_f32_e32 v96, v244, v128
	v_fmac_f32_e32 v97, v244, v136
	v_fmac_f32_e32 v104, v244, v228
	s_waitcnt vmcnt(0)
	v_fmac_f32_e32 v96, v245, v129
	v_fmac_f32_e32 v97, v245, v137
	v_fmac_f32_e32 v104, v245, v229
	v_add_u32_e32 v121, 0x80, v121
	s_cmp_eq_u32 s22, 0x480000
	s_cbranch_scc0 .LBB0_489
	v_fma_f32 v36, v120, v36, 0
	v_fma_f32 v40, v120, v40, 0
	v_fma_f32 v44, v120, v44, 0
	v_fmac_f32_e32 v36, v119, v37
	v_fmac_f32_e32 v40, v119, v41
	v_fmac_f32_e32 v44, v119, v45
	v_fmac_f32_e32 v36, v118, v38
	v_fmac_f32_e32 v40, v118, v42
	v_fmac_f32_e32 v44, v118, v46
	v_fmac_f32_e32 v36, v116, v39
	v_fmac_f32_e32 v40, v116, v43
	v_fmac_f32_e32 v44, v116, v47
	v_fmac_f32_e32 v36, v114, v24
	v_fmac_f32_e32 v40, v114, v28
	v_fmac_f32_e32 v44, v114, v32
	v_fmac_f32_e32 v36, v112, v25
	v_fmac_f32_e32 v40, v112, v29
	v_fmac_f32_e32 v44, v112, v33
	v_fmac_f32_e32 v36, v110, v26
	v_fmac_f32_e32 v40, v110, v30
	v_fmac_f32_e32 v44, v110, v34
	v_fmac_f32_e32 v36, v108, v27
	v_fmac_f32_e32 v40, v108, v31
	v_fmac_f32_e32 v44, v108, v35
	v_fmac_f32_e32 v36, v117, v12
	v_fmac_f32_e32 v40, v117, v16
	v_fmac_f32_e32 v44, v117, v20
	v_fmac_f32_e32 v36, v115, v13
	v_fmac_f32_e32 v40, v115, v17
	v_fmac_f32_e32 v44, v115, v21
	v_fmac_f32_e32 v36, v113, v14
	v_fmac_f32_e32 v40, v113, v18
	v_fmac_f32_e32 v44, v113, v22
	v_fmac_f32_e32 v36, v111, v15
	v_fmac_f32_e32 v40, v111, v19
	v_fmac_f32_e32 v44, v111, v23
	v_fmac_f32_e32 v36, v109, v0
	v_fmac_f32_e32 v40, v109, v4
	v_fmac_f32_e32 v44, v109, v8
	v_fmac_f32_e32 v36, v107, v1
	v_fmac_f32_e32 v40, v107, v5
	v_fmac_f32_e32 v44, v107, v9
	v_fmac_f32_e32 v36, v106, v2
	v_fmac_f32_e32 v40, v106, v6
	v_fmac_f32_e32 v44, v106, v10
	v_fmac_f32_e32 v36, v105, v3
	v_fmac_f32_e32 v40, v105, v7
	v_fmac_f32_e32 v44, v105, v11
	ds_bpermute_b32 v0, v99, v36
	ds_bpermute_b32 v1, v99, v40
	ds_bpermute_b32 v2, v99, v44
	v_add_u32_e32 v6, 0x3000, v98
	ds_write2_b32 v6, v96, v97 offset1:72
	ds_write_b32 v98, v104 offset:12864
	s_waitcnt lgkmcnt(4)
	v_add_f32_e32 v0, v36, v0
	s_waitcnt lgkmcnt(3)
	v_add_f32_e32 v1, v40, v1
	s_waitcnt lgkmcnt(2)
	v_add_f32_e32 v2, v44, v2
	ds_bpermute_b32 v3, v100, v0
	ds_bpermute_b32 v4, v100, v1
	ds_bpermute_b32 v5, v100, v2
	s_waitcnt lgkmcnt(2)
	v_add_f32_e32 v0, v0, v3
	s_waitcnt lgkmcnt(1)
	v_add_f32_e32 v1, v1, v4
	s_waitcnt lgkmcnt(0)
	v_add_f32_e32 v2, v2, v5
	ds_bpermute_b32 v3, v101, v0
	ds_bpermute_b32 v4, v101, v1
	ds_bpermute_b32 v5, v101, v2
	s_and_saveexec_b64 s[8:9], vcc
	s_cbranch_execz .LBB0_492
	s_waitcnt lgkmcnt(2)
	v_add_f32_e32 v0, v0, v3
	s_waitcnt lgkmcnt(1)
	v_add_f32_e32 v1, v1, v4
	s_waitcnt lgkmcnt(0)
	v_add_f32_e32 v2, v2, v5
	ds_write2_b32 v6, v0, v1 offset0:64 offset1:136
	ds_write_b32 v98, v2 offset:13120
